# PLE gate epilogue: rstd and sum-of-squares cross-lane reductions via v_permlane16/32_swap instead of ds_bpermute (32 sites)
# baseline (speedup 1.0000x reference)
.LBB0_948:
	s_lshl_b32 s10, s20, 8
	s_add_i32 s10, s10, s61
	v_mbcnt_lo_u32_b32 v124, -1, 0
	v_mbcnt_hi_u32_b32 v124, -1, v124
	s_nop 0
	v_ashrrev_i32_e32 v122, 1, v124
	v_and_or_b32 v208, v124, 15, s10
	s_lshl_b32 s10, s82, 8
	v_and_b32_e32 v122, -8, v122
	s_or_b32 s10, s10, s68
	v_add_u32_e32 v204, s10, v122
	v_ashrrev_i32_e32 v122, 2, v124
	v_and_b32_e32 v122, -4, v122
	v_ashrrev_i32_e32 v123, 31, v122
	v_ashrrev_i32_e32 v209, 31, v208
	v_ashrrev_i32_e32 v205, 31, v204
	v_lshl_add_u64 v[206:207], v[122:123], 2, s[6:7]
	v_lshlrev_b64 v[122:123], 10, v[208:209]
	v_lshl_add_u64 v[122:123], v[122:123], 0, v[204:205]
	v_lshlrev_b32_e32 v125, 2, v124
	v_lshlrev_b64 v[122:123], 1, v[122:123]
	v_xor_b32_e32 v229, 64, v125
	v_xor_b32_e32 v228, 0x80, v125
	v_cmp_gt_u32_e32 vcc, 16, v124
	v_lshl_add_u64 v[124:125], s[88:89], 0, v[122:123]
	v_lshl_add_u64 v[122:123], s[62:63], 0, v[122:123]
	v_lshlrev_b64 v[226:227], 6, v[208:209]
	global_load_dwordx4 v[190:193], v[124:125], off
	global_load_dwordx4 v[186:189], v[122:123], off
	global_load_dwordx4 v[182:185], v[124:125], off offset:256
	global_load_dwordx4 v[178:181], v[122:123], off offset:256
	v_lshl_add_u64 v[122:123], v[206:207], 0, v[226:227]
	global_load_dwordx4 v[122:125], v[122:123], off
	v_or_b32_e32 v224, 16, v208
	v_ashrrev_i32_e32 v225, 31, v224
	v_lshlrev_b64 v[222:223], 6, v[224:225]
	v_or_b32_e32 v218, 32, v208
	v_ashrrev_i32_e32 v219, 31, v218
	v_lshlrev_b64 v[220:221], 6, v[218:219]
	v_or_b32_e32 v214, 48, v208
	v_ashrrev_i32_e32 v215, 31, v214
	v_lshlrev_b64 v[216:217], 6, v[214:215]
	v_lshl_add_u64 v[210:211], v[206:207], 0, v[216:217]
	s_waitcnt vmcnt(0)
	v_lshlrev_b32_e32 v238, 16, v190
	v_and_b32_e32 v239, 0xffff0000, v190
	v_lshlrev_b32_e32 v190, 16, v191
	v_and_b32_e32 v191, 0xffff0000, v191
	v_mov_b32_e32 v126, v123
	v_mov_b32_e32 v127, v124
	v_mov_b32_e32 v123, v125
	v_pk_add_f32 v[122:123], v[126:127], v[122:123]
	s_nop 0
	v_add_f32_e32 v122, v122, v123
	v_mov_b32_e32 v123, v122
	s_nop 1
	v_permlane16_swap_b32_e32 v123, v122
	s_waitcnt lgkmcnt(0)
	v_add_f32_e32 v122, v122, v123
	v_mov_b32_e32 v123, v122
	s_nop 1
	v_permlane32_swap_b32_e32 v123, v122
	s_waitcnt lgkmcnt(0)
	v_add_f32_e32 v122, v122, v123
	v_fmamk_f32 v122, v122, 0x3a800000, v240
	v_rsq_f32_e32 v236, v122
	v_lshlrev_b64 v[122:123], 10, v[224:225]
	v_lshl_add_u64 v[122:123], v[122:123], 0, v[204:205]
	v_lshlrev_b64 v[122:123], 1, v[122:123]
	v_lshl_add_u64 v[124:125], s[88:89], 0, v[122:123]
	v_lshl_add_u64 v[122:123], s[62:63], 0, v[122:123]
	global_load_dwordx4 v[174:177], v[124:125], off
	global_load_dwordx4 v[170:173], v[122:123], off
	global_load_dwordx4 v[166:169], v[124:125], off offset:256
	global_load_dwordx4 v[162:165], v[122:123], off offset:256
	v_lshl_add_u64 v[122:123], v[206:207], 0, v[222:223]
	global_load_dwordx4 v[122:125], v[122:123], off
	v_mul_f32_e32 v152, v152, v236
	v_mul_f32_e32 v153, v153, v236
	v_mul_f32_e32 v152, 0xbfb8aa3b, v152
	v_mul_f32_e32 v153, 0xbfb8aa3b, v153
	v_mul_f32_e32 v130, v130, v236
	v_mul_f32_e32 v131, v131, v236
	v_exp_f32_e32 v152, v152
	v_exp_f32_e32 v153, v153
	v_mul_f32_e32 v130, 0xbfb8aa3b, v130
	v_mul_f32_e32 v131, 0xbfb8aa3b, v131
	v_exp_f32_e32 v130, v130
	v_exp_f32_e32 v131, v131
	v_add_f32_e32 v152, 1.0, v152
	v_add_f32_e32 v153, 1.0, v153
	v_rcp_f32_e32 v152, v152
	v_rcp_f32_e32 v153, v153
	v_add_f32_e32 v130, 1.0, v130
	v_add_f32_e32 v131, 1.0, v131
	v_rcp_f32_e32 v130, v130
	v_rcp_f32_e32 v131, v131
	v_mul_f32_e32 v150, v150, v236
	v_mul_f32_e32 v151, v151, v236
	v_mul_f32_e32 v150, 0xbfb8aa3b, v150
	v_mul_f32_e32 v151, 0xbfb8aa3b, v151
	v_exp_f32_e32 v150, v150
	v_exp_f32_e32 v151, v151
	v_mul_f32_e32 v118, v118, v236
	v_mul_f32_e32 v119, v119, v236
	v_add_f32_e32 v150, 1.0, v150
	v_add_f32_e32 v151, 1.0, v151
	v_rcp_f32_e32 v150, v150
	v_rcp_f32_e32 v151, v151
	v_mul_f32_e32 v118, 0xbfb8aa3b, v118
	v_mul_f32_e32 v119, 0xbfb8aa3b, v119
	v_mul_f32_e32 v120, v120, v236
	v_mul_f32_e32 v121, v121, v236
	v_exp_f32_e32 v118, v118
	v_exp_f32_e32 v119, v119
	v_mul_f32_e32 v120, 0xbfb8aa3b, v120
	v_mul_f32_e32 v121, 0xbfb8aa3b, v121
	v_mul_f32_e32 v114, v114, v236
	v_mul_f32_e32 v115, v115, v236
	v_exp_f32_e32 v120, v120
	v_exp_f32_e32 v121, v121
	v_mul_f32_e32 v114, 0xbfb8aa3b, v114
	v_mul_f32_e32 v115, 0xbfb8aa3b, v115
	v_exp_f32_e32 v114, v114
	v_exp_f32_e32 v115, v115
	v_add_f32_e32 v118, 1.0, v118
	v_add_f32_e32 v119, 1.0, v119
	v_rcp_f32_e32 v118, v118
	v_rcp_f32_e32 v119, v119
	v_add_f32_e32 v120, 1.0, v120
	v_add_f32_e32 v121, 1.0, v121
	v_rcp_f32_e32 v120, v120
	v_rcp_f32_e32 v121, v121
	v_add_f32_e32 v114, 1.0, v114
	v_add_f32_e32 v115, 1.0, v115
	v_rcp_f32_e32 v114, v114
	v_rcp_f32_e32 v115, v115
	s_waitcnt vmcnt(0)
	v_add_f32_e32 v122, v122, v123
	v_add_f32_e32 v123, v124, v125
	v_add_f32_e32 v122, v122, v123
	v_mov_b32_e32 v123, v122
	s_nop 1
	v_permlane16_swap_b32_e32 v123, v122
	s_waitcnt lgkmcnt(0)
	v_add_f32_e32 v234, v122, v123
	v_lshlrev_b64 v[122:123], 10, v[218:219]
	v_lshl_add_u64 v[122:123], v[122:123], 0, v[204:205]
	v_lshlrev_b64 v[122:123], 1, v[122:123]
	v_lshl_add_u64 v[124:125], s[88:89], 0, v[122:123]
	v_lshl_add_u64 v[122:123], s[62:63], 0, v[122:123]
	global_load_dwordx4 v[158:161], v[124:125], off
	global_load_dwordx4 v[154:157], v[122:123], off
	global_load_dwordx4 v[146:149], v[124:125], off offset:256
	global_load_dwordx4 v[142:145], v[122:123], off offset:256
	v_lshl_add_u64 v[122:123], v[206:207], 0, v[220:221]
	global_load_dwordx4 v[122:125], v[122:123], off
	v_mov_b32_e32 v235, v234
	s_nop 1
	v_permlane32_swap_b32_e32 v235, v234
	s_waitcnt vmcnt(0)
	global_load_dwordx4 v[242:245], v[210:211], off
	v_add_f32_e32 v122, v122, v123
	v_add_f32_e32 v123, v124, v125
	v_add_f32_e32 v122, v122, v123
	v_mov_b32_e32 v123, v122
	s_nop 1
	v_permlane16_swap_b32_e32 v123, v122
	s_waitcnt lgkmcnt(0)
	v_add_f32_e32 v232, v122, v123
	v_lshlrev_b64 v[122:123], 10, v[214:215]
	v_lshl_add_u64 v[122:123], v[122:123], 0, v[204:205]
	v_lshlrev_b64 v[122:123], 1, v[122:123]
	v_lshl_add_u64 v[124:125], s[88:89], 0, v[122:123]
	v_lshl_add_u64 v[122:123], s[62:63], 0, v[122:123]
	global_load_dwordx4 v[138:141], v[124:125], off
	global_load_dwordx4 v[134:137], v[122:123], off
	global_load_dwordx4 v[126:129], v[124:125], off offset:256
	s_nop 0
	global_load_dwordx4 v[122:125], v[122:123], off offset:256
	v_mov_b32_e32 v233, v232
	s_nop 1
	v_permlane32_swap_b32_e32 v233, v232
	s_waitcnt vmcnt(4)
	v_add_f32_e32 v210, v242, v243
	v_lshlrev_b32_e32 v242, 16, v186
	v_and_b32_e32 v243, 0xffff0000, v186
	v_lshlrev_b32_e32 v186, 16, v187
	v_and_b32_e32 v187, 0xffff0000, v187
	v_pk_fma_f32 v[152:153], v[152:153], v[186:187], v[190:191]
	v_lshlrev_b32_e32 v186, 16, v192
	v_and_b32_e32 v187, 0xffff0000, v192
	v_lshlrev_b32_e32 v190, 16, v188
	v_and_b32_e32 v191, 0xffff0000, v188
	v_pk_fma_f32 v[186:187], v[130:131], v[190:191], v[186:187]
	v_mul_f32_e32 v130, v132, v236
	v_mul_f32_e32 v131, v133, v236
	v_mul_f32_e32 v130, 0xbfb8aa3b, v130
	v_mul_f32_e32 v131, 0xbfb8aa3b, v131
	v_exp_f32_e32 v130, v130
	v_exp_f32_e32 v131, v131
	v_add_f32_e32 v211, v244, v245
	v_add_f32_e32 v210, v210, v211
	v_mov_b32_e32 v211, v210
	s_nop 1
	v_permlane16_swap_b32_e32 v211, v210
	v_add_f32_e32 v130, 1.0, v130
	v_add_f32_e32 v131, 1.0, v131
	v_rcp_f32_e32 v130, v130
	v_rcp_f32_e32 v131, v131
	s_waitcnt lgkmcnt(0)
	v_add_f32_e32 v230, v210, v211
	v_lshlrev_b64 v[210:211], 11, v[208:209]
	v_pk_fma_f32 v[150:151], v[150:151], v[242:243], v[238:239]
	v_lshlrev_b32_e32 v132, 16, v193
	v_and_b32_e32 v133, 0xffff0000, v193
	v_lshlrev_b32_e32 v188, 16, v189
	v_and_b32_e32 v189, 0xffff0000, v189
	v_pk_fma_f32 v[188:189], v[130:131], v[188:189], v[132:133]
	v_cvt_pk_bf16_f32 v130, v150, v151
	v_lshl_add_u64 v[150:151], s[92:93], 0, v[210:211]
	v_cvt_pk_bf16_f32 v131, v152, v153
	v_cvt_pk_bf16_f32 v132, v186, v187
	v_cvt_pk_bf16_f32 v133, v188, v189
	v_lshl_add_u64 v[150:151], v[204:205], 1, v[150:151]
	global_store_dwordx4 v[150:151], v[130:133], off
	v_lshlrev_b32_e32 v152, 16, v130
	v_lshlrev_b32_e32 v153, 16, v131
	v_and_b32_e32 v130, 0xffff0000, v130
	v_and_b32_e32 v131, 0xffff0000, v131
	v_mul_f32_e32 v130, v130, v130
	v_mul_f32_e32 v131, v131, v131
	v_lshlrev_b32_e32 v186, 16, v132
	v_and_b32_e32 v132, 0xffff0000, v132
	v_fmac_f32_e32 v130, v152, v152
	v_fmac_f32_e32 v131, v153, v153
	v_add_f32_e32 v130, v130, v131
	v_mul_f32_e32 v131, v132, v132
	v_lshlrev_b32_e32 v187, 16, v133
	v_and_b32_e32 v133, 0xffff0000, v133
	v_fmac_f32_e32 v131, v186, v186
	v_add_f32_e32 v130, v131, v130
	v_mul_f32_e32 v131, v133, v133
	v_fmac_f32_e32 v131, v187, v187
	v_add_f32_e32 v152, v131, v130
	v_lshlrev_b32_e32 v130, 16, v182
	v_and_b32_e32 v131, 0xffff0000, v182
	v_lshlrev_b32_e32 v132, 16, v178
	v_and_b32_e32 v133, 0xffff0000, v178
	v_pk_fma_f32 v[118:119], v[118:119], v[132:133], v[130:131]
	v_lshlrev_b32_e32 v130, 16, v183
	v_and_b32_e32 v131, 0xffff0000, v183
	v_lshlrev_b32_e32 v132, 16, v179
	v_and_b32_e32 v133, 0xffff0000, v179
	v_pk_fma_f32 v[120:121], v[120:121], v[132:133], v[130:131]
	v_lshlrev_b32_e32 v130, 16, v184
	v_and_b32_e32 v131, 0xffff0000, v184
	v_lshlrev_b32_e32 v132, 16, v180
	v_and_b32_e32 v133, 0xffff0000, v180
	v_pk_fma_f32 v[130:131], v[114:115], v[132:133], v[130:131]
	v_mul_f32_e32 v114, v116, v236
	v_mul_f32_e32 v115, v117, v236
	v_mul_f32_e32 v114, 0xbfb8aa3b, v114
	v_mul_f32_e32 v115, 0xbfb8aa3b, v115
	v_exp_f32_e32 v114, v114
	v_exp_f32_e32 v115, v115
	v_lshlrev_b32_e32 v116, 16, v185
	v_and_b32_e32 v117, 0xffff0000, v185
	v_add_f32_e32 v114, 1.0, v114
	v_add_f32_e32 v115, 1.0, v115
	v_rcp_f32_e32 v114, v114
	v_rcp_f32_e32 v115, v115
	v_lshlrev_b32_e32 v132, 16, v181
	v_and_b32_e32 v133, 0xffff0000, v181
	v_mov_b32_e32 v231, v230
	s_nop 1
	v_permlane32_swap_b32_e32 v231, v230
	v_pk_fma_f32 v[132:133], v[114:115], v[132:133], v[116:117]
	v_cvt_pk_bf16_f32 v114, v118, v119
	v_cvt_pk_bf16_f32 v115, v120, v121
	v_cvt_pk_bf16_f32 v116, v130, v131
	v_cvt_pk_bf16_f32 v117, v132, v133
	global_store_dwordx4 v[150:151], v[114:117], off offset:256
	v_lshlrev_b32_e32 v118, 16, v114
	v_lshlrev_b32_e32 v119, 16, v115
	v_and_b32_e32 v114, 0xffff0000, v114
	v_and_b32_e32 v115, 0xffff0000, v115
	v_mul_f32_e32 v114, v114, v114
	v_fmac_f32_e32 v114, v118, v118
	v_mul_f32_e32 v115, v115, v115
	v_lshlrev_b32_e32 v120, 16, v116
	v_and_b32_e32 v116, 0xffff0000, v116
	v_add_f32_e32 v114, v114, v152
	v_fmac_f32_e32 v115, v119, v119
	v_add_f32_e32 v114, v115, v114
	v_mul_f32_e32 v115, v116, v116
	v_lshlrev_b32_e32 v121, 16, v117
	v_and_b32_e32 v117, 0xffff0000, v117
	v_fmac_f32_e32 v115, v120, v120
	v_add_f32_e32 v114, v115, v114
	v_mul_f32_e32 v115, v117, v117
	v_fmac_f32_e32 v115, v121, v121
	v_add_f32_e32 v114, v115, v114
	v_mov_b32_e32 v115, v114
	s_nop 1
	v_permlane16_swap_b32_e32 v115, v114
	s_waitcnt lgkmcnt(0)
	v_add_f32_e32 v114, v114, v115
	v_mov_b32_e32 v115, v114
	s_nop 1
	v_permlane32_swap_b32_e32 v115, v114
	s_and_saveexec_b64 s[10:11], vcc
	s_cbranch_execz .LBB0_950
	s_lshl_b32 s20, s82, 2
	v_lshl_add_u64 v[116:117], s[4:5], 0, v[226:227]
	s_ashr_i32 s21, s20, 31
	v_lshl_add_u64 v[116:117], s[20:21], 2, v[116:117]
	s_lshl_b32 s76, s19, 2
	v_lshl_add_u64 v[116:117], v[116:117], 0, s[76:77]
	s_waitcnt lgkmcnt(0)
	v_add_f32_e32 v114, v114, v115
	global_store_dword v[116:117], v114, off
.LBB0_950:
	s_or_b64 exec, exec, s[10:11]
	v_add_f32_e32 v114, v234, v235
	v_fmamk_f32 v114, v114, 0x3a800000, v240
	v_rsq_f32_e32 v118, v114
	v_lshlrev_b32_e32 v116, 16, v170
	v_and_b32_e32 v117, 0xffff0000, v170
	v_mul_f32_e32 v110, v110, v118
	v_mul_f32_e32 v111, v111, v118
	v_mul_f32_e32 v110, 0xbfb8aa3b, v110
	v_mul_f32_e32 v111, 0xbfb8aa3b, v111
	v_mul_f32_e32 v112, v112, v118
	v_mul_f32_e32 v113, v113, v118
	v_exp_f32_e32 v114, v110
	v_exp_f32_e32 v111, v111
	v_mul_f32_e32 v112, 0xbfb8aa3b, v112
	v_mul_f32_e32 v113, 0xbfb8aa3b, v113
	v_mul_f32_e32 v106, v106, v118
	v_mul_f32_e32 v107, v107, v118
	v_exp_f32_e32 v112, v112
	v_exp_f32_e32 v113, v113
	v_mul_f32_e32 v106, 0xbfb8aa3b, v106
	v_mul_f32_e32 v107, 0xbfb8aa3b, v107
	v_exp_f32_e32 v106, v106
	v_exp_f32_e32 v107, v107
	v_mul_f32_e32 v108, v108, v118
	v_add_f32_e32 v114, 1.0, v114
	v_add_f32_e32 v111, 1.0, v111
	v_mul_f32_e32 v108, 0xbfb8aa3b, v108
	v_rcp_f32_e32 v114, v114
	s_waitcnt lgkmcnt(0)
	v_rcp_f32_e32 v115, v111
	v_add_f32_e32 v112, 1.0, v112
	v_add_f32_e32 v113, 1.0, v113
	v_exp_f32_e32 v119, v108
	v_mul_f32_e32 v108, v109, v118
	v_rcp_f32_e32 v112, v112
	v_rcp_f32_e32 v113, v113
	v_add_f32_e32 v106, 1.0, v106
	v_add_f32_e32 v107, 1.0, v107
	v_mul_f32_e32 v108, 0xbfb8aa3b, v108
	v_rcp_f32_e32 v106, v106
	v_rcp_f32_e32 v107, v107
	v_exp_f32_e32 v120, v108
	v_lshlrev_b32_e32 v110, 16, v174
	v_and_b32_e32 v111, 0xffff0000, v174
	v_pk_fma_f32 v[110:111], v[114:115], v[116:117], v[110:111]
	v_lshlrev_b32_e32 v114, 16, v175
	v_and_b32_e32 v115, 0xffff0000, v175
	v_lshlrev_b32_e32 v116, 16, v171
	v_and_b32_e32 v117, 0xffff0000, v171
	v_pk_fma_f32 v[112:113], v[112:113], v[116:117], v[114:115]
	v_lshlrev_b32_e32 v114, 16, v176
	v_and_b32_e32 v115, 0xffff0000, v176
	v_lshlrev_b32_e32 v116, 16, v172
	v_and_b32_e32 v117, 0xffff0000, v172
	v_pk_fma_f32 v[108:109], v[106:107], v[116:117], v[114:115]
	v_add_f32_e32 v106, 1.0, v119
	v_add_f32_e32 v107, 1.0, v120
	v_rcp_f32_e32 v106, v106
	v_rcp_f32_e32 v107, v107
	v_lshlrev_b32_e32 v114, 16, v177
	v_and_b32_e32 v115, 0xffff0000, v177
	v_lshlrev_b32_e32 v116, 16, v173
	v_and_b32_e32 v117, 0xffff0000, v173
	v_pk_fma_f32 v[114:115], v[106:107], v[116:117], v[114:115]
	v_cvt_pk_bf16_f32 v106, v110, v111
	v_mul_f32_e32 v102, v102, v118
	v_mul_f32_e32 v103, v103, v118
	v_cvt_pk_bf16_f32 v107, v112, v113
	v_and_b32_e32 v111, 0xffff0000, v106
	v_mul_f32_e32 v102, 0xbfb8aa3b, v102
	v_mul_f32_e32 v103, 0xbfb8aa3b, v103
	v_mul_f32_e32 v104, v104, v118
	v_mul_f32_e32 v105, v105, v118
	v_lshlrev_b32_e32 v110, 16, v106
	v_and_b32_e32 v113, 0xffff0000, v107
	v_mul_f32_e32 v111, v111, v111
	v_exp_f32_e32 v102, v102
	v_exp_f32_e32 v103, v103
	v_mul_f32_e32 v104, 0xbfb8aa3b, v104
	v_mul_f32_e32 v105, 0xbfb8aa3b, v105
	v_cvt_pk_bf16_f32 v108, v108, v109
	v_lshlrev_b32_e32 v112, 16, v107
	v_fmac_f32_e32 v111, v110, v110
	v_mul_f32_e32 v110, v113, v113
	v_exp_f32_e32 v104, v104
	v_exp_f32_e32 v105, v105
	v_cvt_pk_bf16_f32 v109, v114, v115
	v_and_b32_e32 v115, 0xffff0000, v108
	v_fmac_f32_e32 v110, v112, v112
	v_mul_f32_e32 v98, v98, v118
	v_lshlrev_b32_e32 v114, 16, v108
	v_add_f32_e32 v110, v111, v110
	v_mul_f32_e32 v111, v115, v115
	v_mul_f32_e32 v98, 0xbfb8aa3b, v98
	v_and_b32_e32 v117, 0xffff0000, v109
	v_fmac_f32_e32 v111, v114, v114
	v_add_f32_e32 v102, 1.0, v102
	v_add_f32_e32 v103, 1.0, v103
	v_exp_f32_e32 v115, v98
	v_mul_f32_e32 v98, v99, v118
	v_lshlrev_b32_e32 v116, 16, v109
	v_add_f32_e32 v110, v111, v110
	v_mul_f32_e32 v111, v117, v117
	v_rcp_f32_e32 v102, v102
	v_rcp_f32_e32 v103, v103
	v_add_f32_e32 v104, 1.0, v104
	v_add_f32_e32 v105, 1.0, v105
	v_mul_f32_e32 v98, 0xbfb8aa3b, v98
	v_mul_f32_e32 v100, v100, v118
	v_mul_f32_e32 v101, v101, v118
	v_fmac_f32_e32 v111, v116, v116
	v_rcp_f32_e32 v104, v104
	v_rcp_f32_e32 v105, v105
	v_exp_f32_e32 v116, v98
	v_mul_f32_e32 v100, 0xbfb8aa3b, v100
	v_mul_f32_e32 v101, 0xbfb8aa3b, v101
	v_exp_f32_e32 v100, v100
	v_exp_f32_e32 v101, v101
	v_add_f32_e32 v114, v111, v110
	v_lshlrev_b32_e32 v110, 16, v166
	v_and_b32_e32 v111, 0xffff0000, v166
	v_lshlrev_b32_e32 v112, 16, v162
	v_and_b32_e32 v113, 0xffff0000, v162
	v_pk_fma_f32 v[102:103], v[102:103], v[112:113], v[110:111]
	v_lshlrev_b32_e32 v110, 16, v167
	v_and_b32_e32 v111, 0xffff0000, v167
	v_lshlrev_b32_e32 v112, 16, v163
	v_and_b32_e32 v113, 0xffff0000, v163
	v_pk_fma_f32 v[98:99], v[104:105], v[112:113], v[110:111]
	v_add_f32_e32 v104, 1.0, v115
	v_add_f32_e32 v105, 1.0, v116
	v_rcp_f32_e32 v104, v104
	v_rcp_f32_e32 v105, v105
	v_add_f32_e32 v100, 1.0, v100
	v_add_f32_e32 v101, 1.0, v101
	v_rcp_f32_e32 v100, v100
	v_rcp_f32_e32 v101, v101
	v_lshlrev_b32_e32 v110, 16, v168
	v_and_b32_e32 v111, 0xffff0000, v168
	v_lshlrev_b32_e32 v112, 16, v164
	v_and_b32_e32 v113, 0xffff0000, v164
	v_pk_fma_f32 v[104:105], v[104:105], v[112:113], v[110:111]
	v_lshlrev_b32_e32 v110, 16, v169
	v_and_b32_e32 v111, 0xffff0000, v169
	v_lshlrev_b32_e32 v112, 16, v165
	v_and_b32_e32 v113, 0xffff0000, v165
	v_pk_fma_f32 v[110:111], v[100:101], v[112:113], v[110:111]
	v_cvt_pk_bf16_f32 v100, v102, v103
	v_cvt_pk_bf16_f32 v101, v98, v99
	v_and_b32_e32 v99, 0xffff0000, v100
	v_lshlrev_b32_e32 v98, 16, v100
	v_mul_f32_e32 v99, v99, v99
	v_cvt_pk_bf16_f32 v102, v104, v105
	v_and_b32_e32 v105, 0xffff0000, v101
	v_fmac_f32_e32 v99, v98, v98
	v_lshlrev_b32_e32 v104, 16, v101
	v_add_f32_e32 v98, v99, v114
	v_mul_f32_e32 v99, v105, v105
	v_cvt_pk_bf16_f32 v103, v110, v111
	v_and_b32_e32 v111, 0xffff0000, v102
	v_fmac_f32_e32 v99, v104, v104
	v_lshlrev_b32_e32 v110, 16, v102
	v_add_f32_e32 v98, v99, v98
	v_mul_f32_e32 v99, v111, v111
	v_and_b32_e32 v113, 0xffff0000, v103
	v_fmac_f32_e32 v99, v110, v110
	v_lshlrev_b32_e32 v112, 16, v103
	v_add_f32_e32 v98, v99, v98
	v_mul_f32_e32 v99, v113, v113
	v_fmac_f32_e32 v99, v112, v112
	v_add_f32_e32 v98, v99, v98
	v_mov_b32_e32 v99, v98
	s_nop 1
	v_permlane16_swap_b32_e32 v99, v98
	v_lshlrev_b64 v[104:105], 11, v[224:225]
	v_lshl_add_u64 v[104:105], s[92:93], 0, v[104:105]
	v_lshl_add_u64 v[104:105], v[204:205], 1, v[104:105]
	global_store_dwordx4 v[104:105], v[106:109], off
	global_store_dwordx4 v[104:105], v[100:103], off offset:256
	s_waitcnt lgkmcnt(0)
	v_add_f32_e32 v98, v98, v99
	v_mov_b32_e32 v99, v98
	s_nop 1
	v_permlane32_swap_b32_e32 v99, v98
	s_and_saveexec_b64 s[10:11], vcc
	s_cbranch_execz .LBB0_952
	s_lshl_b32 s20, s82, 2
	v_lshl_add_u64 v[100:101], s[4:5], 0, v[222:223]
	s_ashr_i32 s21, s20, 31
	v_lshl_add_u64 v[100:101], s[20:21], 2, v[100:101]
	s_lshl_b32 s76, s19, 2
	v_lshl_add_u64 v[100:101], v[100:101], 0, s[76:77]
	s_waitcnt lgkmcnt(0)
	v_add_f32_e32 v98, v98, v99
	global_store_dword v[100:101], v98, off
.LBB0_952:
	s_or_b64 exec, exec, s[10:11]
	v_add_f32_e32 v98, v232, v233
	v_fmamk_f32 v98, v98, 0x3a800000, v240
	v_rsq_f32_e32 v102, v98
	v_lshlrev_b32_e32 v100, 16, v154
	v_and_b32_e32 v101, 0xffff0000, v154
	v_mul_f32_e32 v94, v94, v102
	v_mul_f32_e32 v95, v95, v102
	v_mul_f32_e32 v94, 0xbfb8aa3b, v94
	v_mul_f32_e32 v95, 0xbfb8aa3b, v95
	v_mul_f32_e32 v96, v96, v102
	v_mul_f32_e32 v97, v97, v102
	v_exp_f32_e32 v98, v94
	v_exp_f32_e32 v95, v95
	v_mul_f32_e32 v96, 0xbfb8aa3b, v96
	v_mul_f32_e32 v97, 0xbfb8aa3b, v97
	v_mul_f32_e32 v90, v90, v102
	v_mul_f32_e32 v91, v91, v102
	v_exp_f32_e32 v96, v96
	v_exp_f32_e32 v97, v97
	v_mul_f32_e32 v90, 0xbfb8aa3b, v90
	v_mul_f32_e32 v91, 0xbfb8aa3b, v91
	v_exp_f32_e32 v90, v90
	v_exp_f32_e32 v91, v91
	v_mul_f32_e32 v92, v92, v102
	v_add_f32_e32 v98, 1.0, v98
	v_add_f32_e32 v95, 1.0, v95
	v_mul_f32_e32 v92, 0xbfb8aa3b, v92
	v_rcp_f32_e32 v98, v98
	s_waitcnt lgkmcnt(0)
	v_rcp_f32_e32 v99, v95
	v_add_f32_e32 v96, 1.0, v96
	v_add_f32_e32 v97, 1.0, v97
	v_exp_f32_e32 v103, v92
	v_mul_f32_e32 v92, v93, v102
	v_rcp_f32_e32 v96, v96
	v_rcp_f32_e32 v97, v97
	v_add_f32_e32 v90, 1.0, v90
	v_add_f32_e32 v91, 1.0, v91
	v_mul_f32_e32 v92, 0xbfb8aa3b, v92
	v_rcp_f32_e32 v90, v90
	v_rcp_f32_e32 v91, v91
	v_exp_f32_e32 v104, v92
	v_lshlrev_b32_e32 v94, 16, v158
	v_and_b32_e32 v95, 0xffff0000, v158
	v_pk_fma_f32 v[94:95], v[98:99], v[100:101], v[94:95]
	v_lshlrev_b32_e32 v98, 16, v159
	v_and_b32_e32 v99, 0xffff0000, v159
	v_lshlrev_b32_e32 v100, 16, v155
	v_and_b32_e32 v101, 0xffff0000, v155
	v_pk_fma_f32 v[96:97], v[96:97], v[100:101], v[98:99]
	v_lshlrev_b32_e32 v98, 16, v160
	v_and_b32_e32 v99, 0xffff0000, v160
	v_lshlrev_b32_e32 v100, 16, v156
	v_and_b32_e32 v101, 0xffff0000, v156
	v_pk_fma_f32 v[92:93], v[90:91], v[100:101], v[98:99]
	v_add_f32_e32 v90, 1.0, v103
	v_add_f32_e32 v91, 1.0, v104
	v_rcp_f32_e32 v90, v90
	v_rcp_f32_e32 v91, v91
	v_lshlrev_b32_e32 v98, 16, v161
	v_and_b32_e32 v99, 0xffff0000, v161
	v_lshlrev_b32_e32 v100, 16, v157
	v_and_b32_e32 v101, 0xffff0000, v157
	v_pk_fma_f32 v[98:99], v[90:91], v[100:101], v[98:99]
	v_cvt_pk_bf16_f32 v90, v94, v95
	v_mul_f32_e32 v86, v86, v102
	v_mul_f32_e32 v87, v87, v102
	v_cvt_pk_bf16_f32 v91, v96, v97
	v_and_b32_e32 v95, 0xffff0000, v90
	v_mul_f32_e32 v86, 0xbfb8aa3b, v86
	v_mul_f32_e32 v87, 0xbfb8aa3b, v87
	v_mul_f32_e32 v88, v88, v102
	v_mul_f32_e32 v89, v89, v102
	v_lshlrev_b32_e32 v94, 16, v90
	v_and_b32_e32 v97, 0xffff0000, v91
	v_mul_f32_e32 v95, v95, v95
	v_exp_f32_e32 v86, v86
	v_exp_f32_e32 v87, v87
	v_mul_f32_e32 v88, 0xbfb8aa3b, v88
	v_mul_f32_e32 v89, 0xbfb8aa3b, v89
	v_cvt_pk_bf16_f32 v92, v92, v93
	v_lshlrev_b32_e32 v96, 16, v91
	v_fmac_f32_e32 v95, v94, v94
	v_mul_f32_e32 v94, v97, v97
	v_exp_f32_e32 v88, v88
	v_exp_f32_e32 v89, v89
	v_cvt_pk_bf16_f32 v93, v98, v99
	v_and_b32_e32 v99, 0xffff0000, v92
	v_fmac_f32_e32 v94, v96, v96
	v_mul_f32_e32 v82, v82, v102
	v_lshlrev_b32_e32 v98, 16, v92
	v_add_f32_e32 v94, v95, v94
	v_mul_f32_e32 v95, v99, v99
	v_mul_f32_e32 v82, 0xbfb8aa3b, v82
	v_and_b32_e32 v101, 0xffff0000, v93
	v_fmac_f32_e32 v95, v98, v98
	v_add_f32_e32 v86, 1.0, v86
	v_add_f32_e32 v87, 1.0, v87
	v_exp_f32_e32 v99, v82
	v_mul_f32_e32 v82, v83, v102
	v_lshlrev_b32_e32 v100, 16, v93
	v_add_f32_e32 v94, v95, v94
	v_mul_f32_e32 v95, v101, v101
	v_rcp_f32_e32 v86, v86
	v_rcp_f32_e32 v87, v87
	v_add_f32_e32 v88, 1.0, v88
	v_add_f32_e32 v89, 1.0, v89
	v_mul_f32_e32 v82, 0xbfb8aa3b, v82
	v_mul_f32_e32 v84, v84, v102
	v_mul_f32_e32 v85, v85, v102
	v_fmac_f32_e32 v95, v100, v100
	v_rcp_f32_e32 v88, v88
	v_rcp_f32_e32 v89, v89
	v_exp_f32_e32 v100, v82
	v_mul_f32_e32 v84, 0xbfb8aa3b, v84
	v_mul_f32_e32 v85, 0xbfb8aa3b, v85
	v_exp_f32_e32 v84, v84
	v_exp_f32_e32 v85, v85
	v_add_f32_e32 v98, v95, v94
	v_lshlrev_b32_e32 v94, 16, v146
	v_and_b32_e32 v95, 0xffff0000, v146
	v_lshlrev_b32_e32 v96, 16, v142
	v_and_b32_e32 v97, 0xffff0000, v142
	v_pk_fma_f32 v[86:87], v[86:87], v[96:97], v[94:95]
	v_lshlrev_b32_e32 v94, 16, v147
	v_and_b32_e32 v95, 0xffff0000, v147
	v_lshlrev_b32_e32 v96, 16, v143
	v_and_b32_e32 v97, 0xffff0000, v143
	v_pk_fma_f32 v[82:83], v[88:89], v[96:97], v[94:95]
	v_add_f32_e32 v88, 1.0, v99
	v_add_f32_e32 v89, 1.0, v100
	v_rcp_f32_e32 v88, v88
	v_rcp_f32_e32 v89, v89
	v_add_f32_e32 v84, 1.0, v84
	v_add_f32_e32 v85, 1.0, v85
	v_rcp_f32_e32 v84, v84
	v_rcp_f32_e32 v85, v85
	v_lshlrev_b32_e32 v94, 16, v148
	v_and_b32_e32 v95, 0xffff0000, v148
	v_lshlrev_b32_e32 v96, 16, v144
	v_and_b32_e32 v97, 0xffff0000, v144
	v_pk_fma_f32 v[88:89], v[88:89], v[96:97], v[94:95]
	v_lshlrev_b32_e32 v94, 16, v149
	v_and_b32_e32 v95, 0xffff0000, v149
	v_lshlrev_b32_e32 v96, 16, v145
	v_and_b32_e32 v97, 0xffff0000, v145
	v_pk_fma_f32 v[94:95], v[84:85], v[96:97], v[94:95]
	v_cvt_pk_bf16_f32 v84, v86, v87
	v_cvt_pk_bf16_f32 v85, v82, v83
	v_and_b32_e32 v83, 0xffff0000, v84
	v_lshlrev_b32_e32 v82, 16, v84
	v_mul_f32_e32 v83, v83, v83
	v_cvt_pk_bf16_f32 v86, v88, v89
	v_and_b32_e32 v89, 0xffff0000, v85
	v_fmac_f32_e32 v83, v82, v82
	v_lshlrev_b32_e32 v88, 16, v85
	v_add_f32_e32 v82, v83, v98
	v_mul_f32_e32 v83, v89, v89
	v_cvt_pk_bf16_f32 v87, v94, v95
	v_and_b32_e32 v95, 0xffff0000, v86
	v_fmac_f32_e32 v83, v88, v88
	v_lshlrev_b32_e32 v94, 16, v86
	v_add_f32_e32 v82, v83, v82
	v_mul_f32_e32 v83, v95, v95
	v_and_b32_e32 v97, 0xffff0000, v87
	v_fmac_f32_e32 v83, v94, v94
	v_lshlrev_b32_e32 v96, 16, v87
	v_add_f32_e32 v82, v83, v82
	v_mul_f32_e32 v83, v97, v97
	v_fmac_f32_e32 v83, v96, v96
	v_add_f32_e32 v82, v83, v82
	v_mov_b32_e32 v83, v82
	s_nop 1
	v_permlane16_swap_b32_e32 v83, v82
	v_lshlrev_b64 v[88:89], 11, v[218:219]
	v_lshl_add_u64 v[88:89], s[92:93], 0, v[88:89]
	v_lshl_add_u64 v[88:89], v[204:205], 1, v[88:89]
	global_store_dwordx4 v[88:89], v[90:93], off
	global_store_dwordx4 v[88:89], v[84:87], off offset:256
	s_waitcnt lgkmcnt(0)
	v_add_f32_e32 v82, v82, v83
	v_mov_b32_e32 v83, v82
	s_nop 1
	v_permlane32_swap_b32_e32 v83, v82
	s_and_saveexec_b64 s[10:11], vcc
	s_cbranch_execz .LBB0_954
	s_lshl_b32 s20, s82, 2
	v_lshl_add_u64 v[84:85], s[4:5], 0, v[220:221]
	s_ashr_i32 s21, s20, 31
	v_lshl_add_u64 v[84:85], s[20:21], 2, v[84:85]
	s_lshl_b32 s76, s19, 2
	v_lshl_add_u64 v[84:85], v[84:85], 0, s[76:77]
	s_waitcnt lgkmcnt(0)
	v_add_f32_e32 v82, v82, v83
	global_store_dword v[84:85], v82, off
.LBB0_954:
	s_or_b64 exec, exec, s[10:11]
	v_add_f32_e32 v82, v230, v231
	v_fmamk_f32 v82, v82, 0x3a800000, v240
	v_rsq_f32_e32 v86, v82
	s_waitcnt vmcnt(11)
	v_lshlrev_b32_e32 v84, 16, v134
	v_and_b32_e32 v85, 0xffff0000, v134
	v_mul_f32_e32 v78, v78, v86
	v_mul_f32_e32 v79, v79, v86
	v_mul_f32_e32 v78, 0xbfb8aa3b, v78
	v_mul_f32_e32 v79, 0xbfb8aa3b, v79
	v_mul_f32_e32 v80, v80, v86
	v_mul_f32_e32 v81, v81, v86
	v_exp_f32_e32 v82, v78
	v_exp_f32_e32 v79, v79
	v_mul_f32_e32 v80, 0xbfb8aa3b, v80
	v_mul_f32_e32 v81, 0xbfb8aa3b, v81
	v_mul_f32_e32 v74, v74, v86
	v_mul_f32_e32 v75, v75, v86
	v_exp_f32_e32 v80, v80
	v_exp_f32_e32 v81, v81
	v_mul_f32_e32 v74, 0xbfb8aa3b, v74
	v_mul_f32_e32 v75, 0xbfb8aa3b, v75
	v_exp_f32_e32 v74, v74
	v_exp_f32_e32 v75, v75
	v_mul_f32_e32 v76, v76, v86
	v_add_f32_e32 v82, 1.0, v82
	v_add_f32_e32 v79, 1.0, v79
	v_mul_f32_e32 v76, 0xbfb8aa3b, v76
	v_rcp_f32_e32 v82, v82
	s_waitcnt lgkmcnt(0)
	v_rcp_f32_e32 v83, v79
	v_add_f32_e32 v80, 1.0, v80
	v_add_f32_e32 v81, 1.0, v81
	v_exp_f32_e32 v87, v76
	v_mul_f32_e32 v76, v77, v86
	v_rcp_f32_e32 v80, v80
	v_rcp_f32_e32 v81, v81
	v_add_f32_e32 v74, 1.0, v74
	v_add_f32_e32 v75, 1.0, v75
	v_mul_f32_e32 v76, 0xbfb8aa3b, v76
	v_rcp_f32_e32 v74, v74
	v_rcp_f32_e32 v75, v75
	v_exp_f32_e32 v88, v76
	v_lshlrev_b32_e32 v78, 16, v138
	v_and_b32_e32 v79, 0xffff0000, v138
	v_pk_fma_f32 v[78:79], v[82:83], v[84:85], v[78:79]
	v_lshlrev_b32_e32 v82, 16, v139
	v_and_b32_e32 v83, 0xffff0000, v139
	v_lshlrev_b32_e32 v84, 16, v135
	v_and_b32_e32 v85, 0xffff0000, v135
	v_pk_fma_f32 v[80:81], v[80:81], v[84:85], v[82:83]
	v_lshlrev_b32_e32 v82, 16, v140
	v_and_b32_e32 v83, 0xffff0000, v140
	v_lshlrev_b32_e32 v84, 16, v136
	v_and_b32_e32 v85, 0xffff0000, v136
	v_pk_fma_f32 v[76:77], v[74:75], v[84:85], v[82:83]
	v_add_f32_e32 v74, 1.0, v87
	v_add_f32_e32 v75, 1.0, v88
	v_rcp_f32_e32 v74, v74
	v_rcp_f32_e32 v75, v75
	v_lshlrev_b32_e32 v82, 16, v141
	v_and_b32_e32 v83, 0xffff0000, v141
	v_lshlrev_b32_e32 v84, 16, v137
	v_and_b32_e32 v85, 0xffff0000, v137
	v_pk_fma_f32 v[82:83], v[74:75], v[84:85], v[82:83]
	v_cvt_pk_bf16_f32 v74, v78, v79
	v_mul_f32_e32 v70, v70, v86
	v_mul_f32_e32 v71, v71, v86
	v_cvt_pk_bf16_f32 v75, v80, v81
	v_and_b32_e32 v79, 0xffff0000, v74
	v_mul_f32_e32 v70, 0xbfb8aa3b, v70
	v_mul_f32_e32 v71, 0xbfb8aa3b, v71
	v_mul_f32_e32 v72, v72, v86
	v_mul_f32_e32 v73, v73, v86
	v_lshlrev_b32_e32 v78, 16, v74
	v_and_b32_e32 v81, 0xffff0000, v75
	v_mul_f32_e32 v79, v79, v79
	v_exp_f32_e32 v70, v70
	v_exp_f32_e32 v71, v71
	v_mul_f32_e32 v72, 0xbfb8aa3b, v72
	v_mul_f32_e32 v73, 0xbfb8aa3b, v73
	v_cvt_pk_bf16_f32 v76, v76, v77
	v_lshlrev_b32_e32 v80, 16, v75
	v_fmac_f32_e32 v79, v78, v78
	v_mul_f32_e32 v78, v81, v81
	v_exp_f32_e32 v72, v72
	v_exp_f32_e32 v73, v73
	v_cvt_pk_bf16_f32 v77, v82, v83
	v_and_b32_e32 v83, 0xffff0000, v76
	v_fmac_f32_e32 v78, v80, v80
	v_mul_f32_e32 v66, v66, v86
	v_lshlrev_b32_e32 v82, 16, v76
	v_add_f32_e32 v78, v79, v78
	v_mul_f32_e32 v79, v83, v83
	v_mul_f32_e32 v66, 0xbfb8aa3b, v66
	v_and_b32_e32 v85, 0xffff0000, v77
	v_fmac_f32_e32 v79, v82, v82
	v_add_f32_e32 v70, 1.0, v70
	v_add_f32_e32 v71, 1.0, v71
	v_exp_f32_e32 v83, v66
	v_mul_f32_e32 v66, v67, v86
	v_lshlrev_b32_e32 v84, 16, v77
	v_add_f32_e32 v78, v79, v78
	v_mul_f32_e32 v79, v85, v85
	v_rcp_f32_e32 v70, v70
	v_rcp_f32_e32 v71, v71
	v_add_f32_e32 v72, 1.0, v72
	v_add_f32_e32 v73, 1.0, v73
	v_mul_f32_e32 v66, 0xbfb8aa3b, v66
	v_mul_f32_e32 v68, v68, v86
	v_mul_f32_e32 v69, v69, v86
	v_fmac_f32_e32 v79, v84, v84
	v_rcp_f32_e32 v72, v72
	v_rcp_f32_e32 v73, v73
	v_exp_f32_e32 v84, v66
	v_mul_f32_e32 v68, 0xbfb8aa3b, v68
	v_mul_f32_e32 v69, 0xbfb8aa3b, v69
	v_exp_f32_e32 v68, v68
	v_exp_f32_e32 v69, v69
	v_add_f32_e32 v82, v79, v78
	s_waitcnt vmcnt(10)
	v_lshlrev_b32_e32 v78, 16, v126
	v_and_b32_e32 v79, 0xffff0000, v126
	s_waitcnt vmcnt(9)
	v_lshlrev_b32_e32 v80, 16, v122
	v_and_b32_e32 v81, 0xffff0000, v122
	v_pk_fma_f32 v[70:71], v[70:71], v[80:81], v[78:79]
	v_lshlrev_b32_e32 v78, 16, v127
	v_and_b32_e32 v79, 0xffff0000, v127
	v_lshlrev_b32_e32 v80, 16, v123
	v_and_b32_e32 v81, 0xffff0000, v123
	v_pk_fma_f32 v[66:67], v[72:73], v[80:81], v[78:79]
	v_add_f32_e32 v72, 1.0, v83
	v_add_f32_e32 v73, 1.0, v84
	v_rcp_f32_e32 v72, v72
	v_rcp_f32_e32 v73, v73
	v_add_f32_e32 v68, 1.0, v68
	v_add_f32_e32 v69, 1.0, v69
	v_rcp_f32_e32 v68, v68
	v_rcp_f32_e32 v69, v69
	v_lshlrev_b32_e32 v78, 16, v128
	v_and_b32_e32 v79, 0xffff0000, v128
	v_lshlrev_b32_e32 v80, 16, v124
	v_and_b32_e32 v81, 0xffff0000, v124
	v_pk_fma_f32 v[72:73], v[72:73], v[80:81], v[78:79]
	v_lshlrev_b32_e32 v78, 16, v129
	v_and_b32_e32 v79, 0xffff0000, v129
	v_lshlrev_b32_e32 v80, 16, v125
	v_and_b32_e32 v81, 0xffff0000, v125
	v_pk_fma_f32 v[78:79], v[68:69], v[80:81], v[78:79]
	v_cvt_pk_bf16_f32 v68, v70, v71
	v_cvt_pk_bf16_f32 v69, v66, v67
	v_and_b32_e32 v67, 0xffff0000, v68
	v_lshlrev_b32_e32 v66, 16, v68
	v_mul_f32_e32 v67, v67, v67
	v_cvt_pk_bf16_f32 v70, v72, v73
	v_and_b32_e32 v73, 0xffff0000, v69
	v_fmac_f32_e32 v67, v66, v66
	v_lshlrev_b32_e32 v72, 16, v69
	v_add_f32_e32 v66, v67, v82
	v_mul_f32_e32 v67, v73, v73
	v_cvt_pk_bf16_f32 v71, v78, v79
	v_and_b32_e32 v79, 0xffff0000, v70
	v_fmac_f32_e32 v67, v72, v72
	v_lshlrev_b32_e32 v78, 16, v70
	v_add_f32_e32 v66, v67, v66
	v_mul_f32_e32 v67, v79, v79
	v_and_b32_e32 v81, 0xffff0000, v71
	v_fmac_f32_e32 v67, v78, v78
	v_lshlrev_b32_e32 v80, 16, v71
	v_add_f32_e32 v66, v67, v66
	v_mul_f32_e32 v67, v81, v81
	v_fmac_f32_e32 v67, v80, v80
	v_add_f32_e32 v66, v67, v66
	v_mov_b32_e32 v67, v66
	s_nop 1
	v_permlane16_swap_b32_e32 v67, v66
	v_lshlrev_b64 v[72:73], 11, v[214:215]
	v_lshl_add_u64 v[72:73], s[92:93], 0, v[72:73]
	v_lshl_add_u64 v[72:73], v[204:205], 1, v[72:73]
	global_store_dwordx4 v[72:73], v[74:77], off
	global_store_dwordx4 v[72:73], v[68:71], off offset:256
	s_waitcnt lgkmcnt(0)
	v_add_f32_e32 v66, v66, v67
	v_mov_b32_e32 v67, v66
	s_nop 1
	v_permlane32_swap_b32_e32 v67, v66
	s_and_saveexec_b64 s[10:11], vcc
	s_cbranch_execz .LBB0_956
	s_lshl_b32 s20, s82, 2
	v_lshl_add_u64 v[68:69], s[4:5], 0, v[216:217]
	s_ashr_i32 s21, s20, 31
	v_lshl_add_u64 v[68:69], s[20:21], 2, v[68:69]
	s_lshl_b32 s76, s19, 2
	v_lshl_add_u64 v[68:69], v[68:69], 0, s[76:77]
	s_waitcnt lgkmcnt(0)
	v_add_f32_e32 v66, v66, v67
	global_store_dword v[68:69], v66, off
.LBB0_956:
	s_or_b64 exec, exec, s[10:11]
	v_add_u32_e32 v144, 0x80, v208
	v_ashrrev_i32_e32 v145, 31, v144
	s_waitcnt lgkmcnt(0)
	v_lshlrev_b64 v[66:67], 10, v[144:145]
	v_lshl_add_u64 v[66:67], v[66:67], 0, v[204:205]
	v_lshlrev_b64 v[66:67], 1, v[66:67]
	v_lshl_add_u64 v[68:69], s[88:89], 0, v[66:67]
	v_lshl_add_u64 v[66:67], s[62:63], 0, v[66:67]
	v_lshlrev_b64 v[142:143], 6, v[144:145]
	global_load_dwordx4 v[126:129], v[68:69], off
	global_load_dwordx4 v[122:125], v[66:67], off
	global_load_dwordx4 v[118:121], v[68:69], off offset:256
	global_load_dwordx4 v[114:117], v[66:67], off offset:256
	v_lshl_add_u64 v[66:67], v[206:207], 0, v[142:143]
	global_load_dwordx4 v[66:69], v[66:67], off
	v_add_u32_e32 v140, 0x90, v208
	v_ashrrev_i32_e32 v141, 31, v140
	v_lshlrev_b64 v[138:139], 6, v[140:141]
	v_add_u32_e32 v134, 0xa0, v208
	v_ashrrev_i32_e32 v135, 31, v134
	v_lshlrev_b64 v[136:137], 6, v[134:135]
	v_add_u32_e32 v130, 0xb0, v208
	v_ashrrev_i32_e32 v131, 31, v130
	v_lshlrev_b64 v[132:133], 6, v[130:131]
	v_lshl_add_u64 v[146:147], v[206:207], 0, v[132:133]
	v_lshlrev_b64 v[144:145], 11, v[144:145]
	s_waitcnt vmcnt(0)
	v_mov_b32_e32 v70, v67
	v_mov_b32_e32 v71, v68
	v_mov_b32_e32 v67, v69
	v_pk_add_f32 v[66:67], v[70:71], v[66:67]
	s_nop 0
	v_add_f32_e32 v66, v66, v67
	v_mov_b32_e32 v67, v66
	s_nop 1
	v_permlane16_swap_b32_e32 v67, v66
	s_waitcnt lgkmcnt(0)
	v_add_f32_e32 v66, v66, v67
	v_mov_b32_e32 v67, v66
	s_nop 1
	v_permlane32_swap_b32_e32 v67, v66
	s_waitcnt lgkmcnt(0)
	v_add_f32_e32 v66, v66, v67
	v_fmamk_f32 v66, v66, 0x3a800000, v240
	v_rsq_f32_e32 v152, v66
	v_lshlrev_b64 v[66:67], 10, v[140:141]
	v_lshl_add_u64 v[66:67], v[66:67], 0, v[204:205]
	v_lshlrev_b64 v[66:67], 1, v[66:67]
	v_lshl_add_u64 v[68:69], s[88:89], 0, v[66:67]
	v_lshl_add_u64 v[66:67], s[62:63], 0, v[66:67]
	global_load_dwordx4 v[110:113], v[68:69], off
	global_load_dwordx4 v[106:109], v[66:67], off
	global_load_dwordx4 v[102:105], v[68:69], off offset:256
	global_load_dwordx4 v[98:101], v[66:67], off offset:256
	v_lshl_add_u64 v[66:67], v[206:207], 0, v[138:139]
	global_load_dwordx4 v[66:69], v[66:67], off
	v_mul_f32_e32 v64, v64, v152
	v_mul_f32_e32 v65, v65, v152
	v_mul_f32_e32 v64, 0xbfb8aa3b, v64
	v_mul_f32_e32 v65, 0xbfb8aa3b, v65
	v_mul_f32_e32 v58, v58, v152
	v_mul_f32_e32 v59, v59, v152
	v_exp_f32_e32 v64, v64
	v_exp_f32_e32 v65, v65
	v_mul_f32_e32 v58, 0xbfb8aa3b, v58
	v_mul_f32_e32 v59, 0xbfb8aa3b, v59
	v_exp_f32_e32 v58, v58
	v_exp_f32_e32 v59, v59
	v_add_f32_e32 v64, 1.0, v64
	v_add_f32_e32 v65, 1.0, v65
	v_rcp_f32_e32 v64, v64
	v_rcp_f32_e32 v65, v65
	v_add_f32_e32 v58, 1.0, v58
	v_add_f32_e32 v59, 1.0, v59
	v_rcp_f32_e32 v58, v58
	v_rcp_f32_e32 v59, v59
	v_mul_f32_e32 v62, v62, v152
	v_mul_f32_e32 v63, v63, v152
	v_mul_f32_e32 v62, 0xbfb8aa3b, v62
	v_mul_f32_e32 v63, 0xbfb8aa3b, v63
	v_exp_f32_e32 v62, v62
	v_exp_f32_e32 v63, v63
	v_mul_f32_e32 v54, v54, v152
	v_mul_f32_e32 v55, v55, v152
	v_add_f32_e32 v62, 1.0, v62
	v_add_f32_e32 v63, 1.0, v63
	v_rcp_f32_e32 v62, v62
	v_rcp_f32_e32 v63, v63
	v_mul_f32_e32 v54, 0xbfb8aa3b, v54
	v_mul_f32_e32 v55, 0xbfb8aa3b, v55
	v_mul_f32_e32 v56, v56, v152
	v_mul_f32_e32 v57, v57, v152
	v_exp_f32_e32 v54, v54
	v_exp_f32_e32 v55, v55
	v_mul_f32_e32 v56, 0xbfb8aa3b, v56
	v_mul_f32_e32 v57, 0xbfb8aa3b, v57
	v_mul_f32_e32 v50, v50, v152
	v_mul_f32_e32 v51, v51, v152
	v_exp_f32_e32 v56, v56
	v_exp_f32_e32 v57, v57
	v_mul_f32_e32 v50, 0xbfb8aa3b, v50
	v_mul_f32_e32 v51, 0xbfb8aa3b, v51
	v_exp_f32_e32 v50, v50
	v_exp_f32_e32 v51, v51
	v_add_f32_e32 v54, 1.0, v54
	v_add_f32_e32 v55, 1.0, v55
	v_rcp_f32_e32 v54, v54
	v_rcp_f32_e32 v55, v55
	v_add_f32_e32 v56, 1.0, v56
	v_add_f32_e32 v57, 1.0, v57
	v_rcp_f32_e32 v56, v56
	v_rcp_f32_e32 v57, v57
	v_add_f32_e32 v50, 1.0, v50
	v_add_f32_e32 v51, 1.0, v51
	v_rcp_f32_e32 v50, v50
	v_rcp_f32_e32 v51, v51
	s_waitcnt vmcnt(0)
	v_add_f32_e32 v66, v66, v67
	v_add_f32_e32 v67, v68, v69
	v_add_f32_e32 v66, v66, v67
	v_mov_b32_e32 v67, v66
	s_nop 1
	v_permlane16_swap_b32_e32 v67, v66
	s_waitcnt lgkmcnt(0)
	v_add_f32_e32 v150, v66, v67
	v_lshlrev_b64 v[66:67], 10, v[134:135]
	v_lshl_add_u64 v[66:67], v[66:67], 0, v[204:205]
	v_lshlrev_b64 v[66:67], 1, v[66:67]
	v_lshl_add_u64 v[68:69], s[88:89], 0, v[66:67]
	v_lshl_add_u64 v[66:67], s[62:63], 0, v[66:67]
	global_load_dwordx4 v[94:97], v[68:69], off
	global_load_dwordx4 v[90:93], v[66:67], off
	global_load_dwordx4 v[86:89], v[68:69], off offset:256
	global_load_dwordx4 v[82:85], v[66:67], off offset:256
	v_lshl_add_u64 v[66:67], v[206:207], 0, v[136:137]
	global_load_dwordx4 v[66:69], v[66:67], off
	v_mov_b32_e32 v151, v150
	s_nop 1
	v_permlane32_swap_b32_e32 v151, v150
	s_waitcnt vmcnt(0)
	global_load_dwordx4 v[154:157], v[146:147], off
	v_add_f32_e32 v66, v66, v67
	v_add_f32_e32 v67, v68, v69
	v_add_f32_e32 v66, v66, v67
	v_mov_b32_e32 v67, v66
	s_nop 1
	v_permlane16_swap_b32_e32 v67, v66
	s_waitcnt lgkmcnt(0)
	v_add_f32_e32 v148, v66, v67
	v_lshlrev_b64 v[66:67], 10, v[130:131]
	v_lshl_add_u64 v[66:67], v[66:67], 0, v[204:205]
	v_lshlrev_b64 v[66:67], 1, v[66:67]
	v_lshl_add_u64 v[68:69], s[88:89], 0, v[66:67]
	v_lshl_add_u64 v[66:67], s[62:63], 0, v[66:67]
	global_load_dwordx4 v[78:81], v[68:69], off
	global_load_dwordx4 v[74:77], v[66:67], off
	global_load_dwordx4 v[70:73], v[68:69], off offset:256
	s_nop 0
	global_load_dwordx4 v[66:69], v[66:67], off offset:256
	v_mov_b32_e32 v149, v148
	s_nop 1
	v_permlane32_swap_b32_e32 v149, v148
	s_waitcnt vmcnt(4)
	v_add_f32_e32 v146, v154, v155
	v_add_f32_e32 v147, v156, v157
	v_lshlrev_b32_e32 v154, 16, v126
	v_and_b32_e32 v155, 0xffff0000, v126
	v_lshlrev_b32_e32 v156, 16, v122
	v_and_b32_e32 v157, 0xffff0000, v122
	v_lshlrev_b32_e32 v126, 16, v127
	v_and_b32_e32 v127, 0xffff0000, v127
	v_lshlrev_b32_e32 v122, 16, v123
	v_and_b32_e32 v123, 0xffff0000, v123
	v_pk_fma_f32 v[64:65], v[64:65], v[122:123], v[126:127]
	v_lshlrev_b32_e32 v122, 16, v128
	v_and_b32_e32 v123, 0xffff0000, v128
	v_lshlrev_b32_e32 v126, 16, v124
	v_and_b32_e32 v127, 0xffff0000, v124
	v_pk_fma_f32 v[122:123], v[58:59], v[126:127], v[122:123]
	v_mul_f32_e32 v58, v60, v152
	v_mul_f32_e32 v59, v61, v152
	v_mul_f32_e32 v58, 0xbfb8aa3b, v58
	v_mul_f32_e32 v59, 0xbfb8aa3b, v59
	v_exp_f32_e32 v58, v58
	v_exp_f32_e32 v59, v59
	v_pk_fma_f32 v[62:63], v[62:63], v[156:157], v[154:155]
	v_lshlrev_b32_e32 v60, 16, v129
	v_add_f32_e32 v58, 1.0, v58
	v_add_f32_e32 v59, 1.0, v59
	v_rcp_f32_e32 v58, v58
	v_rcp_f32_e32 v59, v59
	v_and_b32_e32 v61, 0xffff0000, v129
	v_lshlrev_b32_e32 v124, 16, v125
	v_and_b32_e32 v125, 0xffff0000, v125
	v_pk_fma_f32 v[124:125], v[58:59], v[124:125], v[60:61]
	v_cvt_pk_bf16_f32 v58, v62, v63
	v_lshl_add_u64 v[62:63], s[92:93], 0, v[144:145]
	v_cvt_pk_bf16_f32 v59, v64, v65
	v_cvt_pk_bf16_f32 v60, v122, v123
	v_cvt_pk_bf16_f32 v61, v124, v125
	v_lshl_add_u64 v[62:63], v[204:205], 1, v[62:63]
	global_store_dwordx4 v[62:63], v[58:61], off
	v_lshlrev_b32_e32 v64, 16, v58
	v_lshlrev_b32_e32 v65, 16, v59
	v_and_b32_e32 v58, 0xffff0000, v58
	v_and_b32_e32 v59, 0xffff0000, v59
	v_mul_f32_e32 v58, v58, v58
	v_mul_f32_e32 v59, v59, v59
	v_lshlrev_b32_e32 v122, 16, v60
	v_and_b32_e32 v60, 0xffff0000, v60
	v_fmac_f32_e32 v58, v64, v64
	v_fmac_f32_e32 v59, v65, v65
	v_add_f32_e32 v58, v58, v59
	v_mul_f32_e32 v59, v60, v60
	v_lshlrev_b32_e32 v123, 16, v61
	v_and_b32_e32 v61, 0xffff0000, v61
	v_fmac_f32_e32 v59, v122, v122
	v_add_f32_e32 v58, v59, v58
	v_mul_f32_e32 v59, v61, v61
	v_fmac_f32_e32 v59, v123, v123
	v_add_f32_e32 v64, v59, v58
	v_lshlrev_b32_e32 v58, 16, v118
	v_and_b32_e32 v59, 0xffff0000, v118
	v_lshlrev_b32_e32 v60, 16, v114
	v_and_b32_e32 v61, 0xffff0000, v114
	v_pk_fma_f32 v[54:55], v[54:55], v[60:61], v[58:59]
	v_lshlrev_b32_e32 v58, 16, v119
	v_and_b32_e32 v59, 0xffff0000, v119
	v_lshlrev_b32_e32 v60, 16, v115
	v_and_b32_e32 v61, 0xffff0000, v115
	v_pk_fma_f32 v[56:57], v[56:57], v[60:61], v[58:59]
	v_lshlrev_b32_e32 v58, 16, v120
	v_and_b32_e32 v59, 0xffff0000, v120
	v_lshlrev_b32_e32 v60, 16, v116
	v_and_b32_e32 v61, 0xffff0000, v116
	v_pk_fma_f32 v[58:59], v[50:51], v[60:61], v[58:59]
	v_mul_f32_e32 v50, v52, v152
	v_mul_f32_e32 v51, v53, v152
	v_mul_f32_e32 v50, 0xbfb8aa3b, v50
	v_mul_f32_e32 v51, 0xbfb8aa3b, v51
	v_exp_f32_e32 v50, v50
	v_exp_f32_e32 v51, v51
	v_lshlrev_b32_e32 v52, 16, v121
	v_and_b32_e32 v53, 0xffff0000, v121
	v_add_f32_e32 v50, 1.0, v50
	v_add_f32_e32 v51, 1.0, v51
	v_rcp_f32_e32 v50, v50
	v_rcp_f32_e32 v51, v51
	v_lshlrev_b32_e32 v60, 16, v117
	v_and_b32_e32 v61, 0xffff0000, v117
	v_add_f32_e32 v146, v146, v147
	v_pk_fma_f32 v[60:61], v[50:51], v[60:61], v[52:53]
	v_cvt_pk_bf16_f32 v50, v54, v55
	v_cvt_pk_bf16_f32 v51, v56, v57
	v_cvt_pk_bf16_f32 v52, v58, v59
	v_cvt_pk_bf16_f32 v53, v60, v61
	global_store_dwordx4 v[62:63], v[50:53], off offset:256
	v_lshlrev_b32_e32 v54, 16, v50
	v_lshlrev_b32_e32 v55, 16, v51
	v_and_b32_e32 v50, 0xffff0000, v50
	v_and_b32_e32 v51, 0xffff0000, v51
	v_mul_f32_e32 v50, v50, v50
	v_fmac_f32_e32 v50, v54, v54
	v_mul_f32_e32 v51, v51, v51
	v_lshlrev_b32_e32 v56, 16, v52
	v_and_b32_e32 v52, 0xffff0000, v52
	v_add_f32_e32 v50, v50, v64
	v_fmac_f32_e32 v51, v55, v55
	v_add_f32_e32 v50, v51, v50
	v_mul_f32_e32 v51, v52, v52
	v_lshlrev_b32_e32 v57, 16, v53
	v_and_b32_e32 v53, 0xffff0000, v53
	v_fmac_f32_e32 v51, v56, v56
	v_add_f32_e32 v50, v51, v50
	v_mul_f32_e32 v51, v53, v53
	v_fmac_f32_e32 v51, v57, v57
	v_add_f32_e32 v50, v51, v50
	v_mov_b32_e32 v147, v146
	s_nop 1
	v_permlane16_swap_b32_e32 v147, v146
	v_mov_b32_e32 v51, v50
	s_nop 1
	v_permlane16_swap_b32_e32 v51, v50
	s_waitcnt lgkmcnt(1)
	v_add_f32_e32 v146, v146, v147
	s_waitcnt lgkmcnt(0)
	v_add_f32_e32 v50, v50, v51
	v_mov_b32_e32 v147, v146
	s_nop 1
	v_permlane32_swap_b32_e32 v147, v146
	v_mov_b32_e32 v51, v50
	s_nop 1
	v_permlane32_swap_b32_e32 v51, v50
	s_and_saveexec_b64 s[10:11], vcc
	s_cbranch_execz .LBB0_958
	s_lshl_b32 s20, s82, 2
	v_lshl_add_u64 v[52:53], s[4:5], 0, v[142:143]
	s_ashr_i32 s21, s20, 31
	v_lshl_add_u64 v[52:53], s[20:21], 2, v[52:53]
	s_lshl_b32 s76, s19, 2
	v_lshl_add_u64 v[52:53], v[52:53], 0, s[76:77]
	s_waitcnt lgkmcnt(0)
	v_add_f32_e32 v50, v50, v51
	global_store_dword v[52:53], v50, off
.LBB0_958:
	s_or_b64 exec, exec, s[10:11]
	v_add_f32_e32 v50, v150, v151
	v_fmamk_f32 v50, v50, 0x3a800000, v240
	v_rsq_f32_e32 v54, v50
	v_lshlrev_b32_e32 v52, 16, v106
	v_and_b32_e32 v53, 0xffff0000, v106
	v_mul_f32_e32 v46, v46, v54
	v_mul_f32_e32 v47, v47, v54
	v_mul_f32_e32 v46, 0xbfb8aa3b, v46
	v_mul_f32_e32 v47, 0xbfb8aa3b, v47
	v_mul_f32_e32 v48, v48, v54
	v_mul_f32_e32 v49, v49, v54
	v_exp_f32_e32 v50, v46
	v_exp_f32_e32 v47, v47
	v_mul_f32_e32 v48, 0xbfb8aa3b, v48
	v_mul_f32_e32 v49, 0xbfb8aa3b, v49
	v_mul_f32_e32 v42, v42, v54
	v_mul_f32_e32 v43, v43, v54
	v_exp_f32_e32 v48, v48
	v_exp_f32_e32 v49, v49
	v_mul_f32_e32 v42, 0xbfb8aa3b, v42
	v_mul_f32_e32 v43, 0xbfb8aa3b, v43
	v_exp_f32_e32 v42, v42
	v_exp_f32_e32 v43, v43
	v_mul_f32_e32 v44, v44, v54
	v_add_f32_e32 v50, 1.0, v50
	v_add_f32_e32 v47, 1.0, v47
	v_mul_f32_e32 v44, 0xbfb8aa3b, v44
	v_rcp_f32_e32 v50, v50
	s_waitcnt lgkmcnt(0)
	v_rcp_f32_e32 v51, v47
	v_add_f32_e32 v48, 1.0, v48
	v_add_f32_e32 v49, 1.0, v49
	v_exp_f32_e32 v55, v44
	v_mul_f32_e32 v44, v45, v54
	v_rcp_f32_e32 v48, v48
	v_rcp_f32_e32 v49, v49
	v_add_f32_e32 v42, 1.0, v42
	v_add_f32_e32 v43, 1.0, v43
	v_mul_f32_e32 v44, 0xbfb8aa3b, v44
	v_rcp_f32_e32 v42, v42
	v_rcp_f32_e32 v43, v43
	v_exp_f32_e32 v56, v44
	v_lshlrev_b32_e32 v46, 16, v110
	v_and_b32_e32 v47, 0xffff0000, v110
	v_pk_fma_f32 v[46:47], v[50:51], v[52:53], v[46:47]
	v_lshlrev_b32_e32 v50, 16, v111
	v_and_b32_e32 v51, 0xffff0000, v111
	v_lshlrev_b32_e32 v52, 16, v107
	v_and_b32_e32 v53, 0xffff0000, v107
	v_pk_fma_f32 v[48:49], v[48:49], v[52:53], v[50:51]
	v_lshlrev_b32_e32 v50, 16, v112
	v_and_b32_e32 v51, 0xffff0000, v112
	v_lshlrev_b32_e32 v52, 16, v108
	v_and_b32_e32 v53, 0xffff0000, v108
	v_pk_fma_f32 v[44:45], v[42:43], v[52:53], v[50:51]
	v_add_f32_e32 v42, 1.0, v55
	v_add_f32_e32 v43, 1.0, v56
	v_rcp_f32_e32 v42, v42
	v_rcp_f32_e32 v43, v43
	v_lshlrev_b32_e32 v50, 16, v113
	v_and_b32_e32 v51, 0xffff0000, v113
	v_lshlrev_b32_e32 v52, 16, v109
	v_and_b32_e32 v53, 0xffff0000, v109
	v_pk_fma_f32 v[50:51], v[42:43], v[52:53], v[50:51]
	v_cvt_pk_bf16_f32 v42, v46, v47
	v_mul_f32_e32 v38, v38, v54
	v_mul_f32_e32 v39, v39, v54
	v_cvt_pk_bf16_f32 v43, v48, v49
	v_and_b32_e32 v47, 0xffff0000, v42
	v_mul_f32_e32 v38, 0xbfb8aa3b, v38
	v_mul_f32_e32 v39, 0xbfb8aa3b, v39
	v_mul_f32_e32 v40, v40, v54
	v_mul_f32_e32 v41, v41, v54
	v_lshlrev_b32_e32 v46, 16, v42
	v_and_b32_e32 v49, 0xffff0000, v43
	v_mul_f32_e32 v47, v47, v47
	v_exp_f32_e32 v38, v38
	v_exp_f32_e32 v39, v39
	v_mul_f32_e32 v40, 0xbfb8aa3b, v40
	v_mul_f32_e32 v41, 0xbfb8aa3b, v41
	v_cvt_pk_bf16_f32 v44, v44, v45
	v_lshlrev_b32_e32 v48, 16, v43
	v_fmac_f32_e32 v47, v46, v46
	v_mul_f32_e32 v46, v49, v49
	v_exp_f32_e32 v40, v40
	v_exp_f32_e32 v41, v41
	v_cvt_pk_bf16_f32 v45, v50, v51
	v_and_b32_e32 v51, 0xffff0000, v44
	v_fmac_f32_e32 v46, v48, v48
	v_mul_f32_e32 v34, v34, v54
	v_lshlrev_b32_e32 v50, 16, v44
	v_add_f32_e32 v46, v47, v46
	v_mul_f32_e32 v47, v51, v51
	v_mul_f32_e32 v34, 0xbfb8aa3b, v34
	v_and_b32_e32 v53, 0xffff0000, v45
	v_fmac_f32_e32 v47, v50, v50
	v_add_f32_e32 v38, 1.0, v38
	v_add_f32_e32 v39, 1.0, v39
	v_exp_f32_e32 v51, v34
	v_mul_f32_e32 v34, v35, v54
	v_lshlrev_b32_e32 v52, 16, v45
	v_add_f32_e32 v46, v47, v46
	v_mul_f32_e32 v47, v53, v53
	v_rcp_f32_e32 v38, v38
	v_rcp_f32_e32 v39, v39
	v_add_f32_e32 v40, 1.0, v40
	v_add_f32_e32 v41, 1.0, v41
	v_mul_f32_e32 v34, 0xbfb8aa3b, v34
	v_mul_f32_e32 v36, v36, v54
	v_mul_f32_e32 v37, v37, v54
	v_fmac_f32_e32 v47, v52, v52
	v_rcp_f32_e32 v40, v40
	v_rcp_f32_e32 v41, v41
	v_exp_f32_e32 v52, v34
	v_mul_f32_e32 v36, 0xbfb8aa3b, v36
	v_mul_f32_e32 v37, 0xbfb8aa3b, v37
	v_exp_f32_e32 v36, v36
	v_exp_f32_e32 v37, v37
	v_add_f32_e32 v50, v47, v46
	v_lshlrev_b32_e32 v46, 16, v102
	v_and_b32_e32 v47, 0xffff0000, v102
	v_lshlrev_b32_e32 v48, 16, v98
	v_and_b32_e32 v49, 0xffff0000, v98
	v_pk_fma_f32 v[38:39], v[38:39], v[48:49], v[46:47]
	v_lshlrev_b32_e32 v46, 16, v103
	v_and_b32_e32 v47, 0xffff0000, v103
	v_lshlrev_b32_e32 v48, 16, v99
	v_and_b32_e32 v49, 0xffff0000, v99
	v_pk_fma_f32 v[34:35], v[40:41], v[48:49], v[46:47]
	v_add_f32_e32 v40, 1.0, v51
	v_add_f32_e32 v41, 1.0, v52
	v_rcp_f32_e32 v40, v40
	v_rcp_f32_e32 v41, v41
	v_add_f32_e32 v36, 1.0, v36
	v_add_f32_e32 v37, 1.0, v37
	v_rcp_f32_e32 v36, v36
	v_rcp_f32_e32 v37, v37
	v_lshlrev_b32_e32 v46, 16, v104
	v_and_b32_e32 v47, 0xffff0000, v104
	v_lshlrev_b32_e32 v48, 16, v100
	v_and_b32_e32 v49, 0xffff0000, v100
	v_pk_fma_f32 v[40:41], v[40:41], v[48:49], v[46:47]
	v_lshlrev_b32_e32 v46, 16, v105
	v_and_b32_e32 v47, 0xffff0000, v105
	v_lshlrev_b32_e32 v48, 16, v101
	v_and_b32_e32 v49, 0xffff0000, v101
	v_pk_fma_f32 v[46:47], v[36:37], v[48:49], v[46:47]
	v_cvt_pk_bf16_f32 v36, v38, v39
	v_cvt_pk_bf16_f32 v37, v34, v35
	v_and_b32_e32 v35, 0xffff0000, v36
	v_lshlrev_b32_e32 v34, 16, v36
	v_mul_f32_e32 v35, v35, v35
	v_cvt_pk_bf16_f32 v38, v40, v41
	v_and_b32_e32 v41, 0xffff0000, v37
	v_fmac_f32_e32 v35, v34, v34
	v_lshlrev_b32_e32 v40, 16, v37
	v_add_f32_e32 v34, v35, v50
	v_mul_f32_e32 v35, v41, v41
	v_cvt_pk_bf16_f32 v39, v46, v47
	v_and_b32_e32 v47, 0xffff0000, v38
	v_fmac_f32_e32 v35, v40, v40
	v_lshlrev_b32_e32 v46, 16, v38
	v_add_f32_e32 v34, v35, v34
	v_mul_f32_e32 v35, v47, v47
	v_and_b32_e32 v49, 0xffff0000, v39
	v_fmac_f32_e32 v35, v46, v46
	v_lshlrev_b32_e32 v48, 16, v39
	v_add_f32_e32 v34, v35, v34
	v_mul_f32_e32 v35, v49, v49
	v_fmac_f32_e32 v35, v48, v48
	v_add_f32_e32 v34, v35, v34
	v_mov_b32_e32 v35, v34
	s_nop 1
	v_permlane16_swap_b32_e32 v35, v34
	v_lshlrev_b64 v[40:41], 11, v[140:141]
	v_lshl_add_u64 v[40:41], s[92:93], 0, v[40:41]
	v_lshl_add_u64 v[40:41], v[204:205], 1, v[40:41]
	global_store_dwordx4 v[40:41], v[42:45], off
	global_store_dwordx4 v[40:41], v[36:39], off offset:256
	s_waitcnt lgkmcnt(0)
	v_add_f32_e32 v34, v34, v35
	v_mov_b32_e32 v35, v34
	s_nop 1
	v_permlane32_swap_b32_e32 v35, v34
	s_and_saveexec_b64 s[10:11], vcc
	s_cbranch_execz .LBB0_960
	s_lshl_b32 s20, s82, 2
	v_lshl_add_u64 v[36:37], s[4:5], 0, v[138:139]
	s_ashr_i32 s21, s20, 31
	v_lshl_add_u64 v[36:37], s[20:21], 2, v[36:37]
	s_lshl_b32 s76, s19, 2
	v_lshl_add_u64 v[36:37], v[36:37], 0, s[76:77]
	s_waitcnt lgkmcnt(0)
	v_add_f32_e32 v34, v34, v35
	global_store_dword v[36:37], v34, off
.LBB0_960:
	s_or_b64 exec, exec, s[10:11]
	v_add_f32_e32 v34, v148, v149
	v_fmamk_f32 v34, v34, 0x3a800000, v240
	v_rsq_f32_e32 v38, v34
	v_lshlrev_b32_e32 v36, 16, v90
	v_and_b32_e32 v37, 0xffff0000, v90
	v_mul_f32_e32 v30, v30, v38
	v_mul_f32_e32 v31, v31, v38
	v_mul_f32_e32 v30, 0xbfb8aa3b, v30
	v_mul_f32_e32 v31, 0xbfb8aa3b, v31
	v_mul_f32_e32 v32, v32, v38
	v_mul_f32_e32 v33, v33, v38
	v_exp_f32_e32 v34, v30
	v_exp_f32_e32 v31, v31
	v_mul_f32_e32 v32, 0xbfb8aa3b, v32
	v_mul_f32_e32 v33, 0xbfb8aa3b, v33
	v_mul_f32_e32 v26, v26, v38
	v_mul_f32_e32 v27, v27, v38
	v_exp_f32_e32 v32, v32
	v_exp_f32_e32 v33, v33
	v_mul_f32_e32 v26, 0xbfb8aa3b, v26
	v_mul_f32_e32 v27, 0xbfb8aa3b, v27
	v_exp_f32_e32 v26, v26
	v_exp_f32_e32 v27, v27
	v_mul_f32_e32 v28, v28, v38
	v_add_f32_e32 v34, 1.0, v34
	v_add_f32_e32 v31, 1.0, v31
	v_mul_f32_e32 v28, 0xbfb8aa3b, v28
	v_rcp_f32_e32 v34, v34
	s_waitcnt lgkmcnt(0)
	v_rcp_f32_e32 v35, v31
	v_add_f32_e32 v32, 1.0, v32
	v_add_f32_e32 v33, 1.0, v33
	v_exp_f32_e32 v39, v28
	v_mul_f32_e32 v28, v29, v38
	v_rcp_f32_e32 v32, v32
	v_rcp_f32_e32 v33, v33
	v_add_f32_e32 v26, 1.0, v26
	v_add_f32_e32 v27, 1.0, v27
	v_mul_f32_e32 v28, 0xbfb8aa3b, v28
	v_rcp_f32_e32 v26, v26
	v_rcp_f32_e32 v27, v27
	v_exp_f32_e32 v40, v28
	v_lshlrev_b32_e32 v30, 16, v94
	v_and_b32_e32 v31, 0xffff0000, v94
	v_pk_fma_f32 v[30:31], v[34:35], v[36:37], v[30:31]
	v_lshlrev_b32_e32 v34, 16, v95
	v_and_b32_e32 v35, 0xffff0000, v95
	v_lshlrev_b32_e32 v36, 16, v91
	v_and_b32_e32 v37, 0xffff0000, v91
	v_pk_fma_f32 v[32:33], v[32:33], v[36:37], v[34:35]
	v_lshlrev_b32_e32 v34, 16, v96
	v_and_b32_e32 v35, 0xffff0000, v96
	v_lshlrev_b32_e32 v36, 16, v92
	v_and_b32_e32 v37, 0xffff0000, v92
	v_pk_fma_f32 v[28:29], v[26:27], v[36:37], v[34:35]
	v_add_f32_e32 v26, 1.0, v39
	v_add_f32_e32 v27, 1.0, v40
	v_rcp_f32_e32 v26, v26
	v_rcp_f32_e32 v27, v27
	v_lshlrev_b32_e32 v34, 16, v97
	v_and_b32_e32 v35, 0xffff0000, v97
	v_lshlrev_b32_e32 v36, 16, v93
	v_and_b32_e32 v37, 0xffff0000, v93
	v_pk_fma_f32 v[34:35], v[26:27], v[36:37], v[34:35]
	v_cvt_pk_bf16_f32 v26, v30, v31
	v_mul_f32_e32 v22, v22, v38
	v_mul_f32_e32 v23, v23, v38
	v_cvt_pk_bf16_f32 v27, v32, v33
	v_and_b32_e32 v31, 0xffff0000, v26
	v_mul_f32_e32 v22, 0xbfb8aa3b, v22
	v_mul_f32_e32 v23, 0xbfb8aa3b, v23
	v_mul_f32_e32 v24, v24, v38
	v_mul_f32_e32 v25, v25, v38
	v_lshlrev_b32_e32 v30, 16, v26
	v_and_b32_e32 v33, 0xffff0000, v27
	v_mul_f32_e32 v31, v31, v31
	v_exp_f32_e32 v22, v22
	v_exp_f32_e32 v23, v23
	v_mul_f32_e32 v24, 0xbfb8aa3b, v24
	v_mul_f32_e32 v25, 0xbfb8aa3b, v25
	v_cvt_pk_bf16_f32 v28, v28, v29
	v_lshlrev_b32_e32 v32, 16, v27
	v_fmac_f32_e32 v31, v30, v30
	v_mul_f32_e32 v30, v33, v33
	v_exp_f32_e32 v24, v24
	v_exp_f32_e32 v25, v25
	v_cvt_pk_bf16_f32 v29, v34, v35
	v_and_b32_e32 v35, 0xffff0000, v28
	v_fmac_f32_e32 v30, v32, v32
	v_mul_f32_e32 v18, v18, v38
	v_lshlrev_b32_e32 v34, 16, v28
	v_add_f32_e32 v30, v31, v30
	v_mul_f32_e32 v31, v35, v35
	v_mul_f32_e32 v18, 0xbfb8aa3b, v18
	v_and_b32_e32 v37, 0xffff0000, v29
	v_fmac_f32_e32 v31, v34, v34
	v_add_f32_e32 v22, 1.0, v22
	v_add_f32_e32 v23, 1.0, v23
	v_exp_f32_e32 v35, v18
	v_mul_f32_e32 v18, v19, v38
	v_lshlrev_b32_e32 v36, 16, v29
	v_add_f32_e32 v30, v31, v30
	v_mul_f32_e32 v31, v37, v37
	v_rcp_f32_e32 v22, v22
	v_rcp_f32_e32 v23, v23
	v_add_f32_e32 v24, 1.0, v24
	v_add_f32_e32 v25, 1.0, v25
	v_mul_f32_e32 v18, 0xbfb8aa3b, v18
	v_mul_f32_e32 v20, v20, v38
	v_mul_f32_e32 v21, v21, v38
	v_fmac_f32_e32 v31, v36, v36
	v_rcp_f32_e32 v24, v24
	v_rcp_f32_e32 v25, v25
	v_exp_f32_e32 v36, v18
	v_mul_f32_e32 v20, 0xbfb8aa3b, v20
	v_mul_f32_e32 v21, 0xbfb8aa3b, v21
	v_exp_f32_e32 v20, v20
	v_exp_f32_e32 v21, v21
	v_add_f32_e32 v34, v31, v30
	v_lshlrev_b32_e32 v30, 16, v86
	v_and_b32_e32 v31, 0xffff0000, v86
	v_lshlrev_b32_e32 v32, 16, v82
	v_and_b32_e32 v33, 0xffff0000, v82
	v_pk_fma_f32 v[22:23], v[22:23], v[32:33], v[30:31]
	v_lshlrev_b32_e32 v30, 16, v87
	v_and_b32_e32 v31, 0xffff0000, v87
	v_lshlrev_b32_e32 v32, 16, v83
	v_and_b32_e32 v33, 0xffff0000, v83
	v_pk_fma_f32 v[18:19], v[24:25], v[32:33], v[30:31]
	v_add_f32_e32 v24, 1.0, v35
	v_add_f32_e32 v25, 1.0, v36
	v_rcp_f32_e32 v24, v24
	v_rcp_f32_e32 v25, v25
	v_add_f32_e32 v20, 1.0, v20
	v_add_f32_e32 v21, 1.0, v21
	v_rcp_f32_e32 v20, v20
	v_rcp_f32_e32 v21, v21
	v_lshlrev_b32_e32 v30, 16, v88
	v_and_b32_e32 v31, 0xffff0000, v88
	v_lshlrev_b32_e32 v32, 16, v84
	v_and_b32_e32 v33, 0xffff0000, v84
	v_pk_fma_f32 v[24:25], v[24:25], v[32:33], v[30:31]
	v_lshlrev_b32_e32 v30, 16, v89
	v_and_b32_e32 v31, 0xffff0000, v89
	v_lshlrev_b32_e32 v32, 16, v85
	v_and_b32_e32 v33, 0xffff0000, v85
	v_pk_fma_f32 v[30:31], v[20:21], v[32:33], v[30:31]
	v_cvt_pk_bf16_f32 v20, v22, v23
	v_cvt_pk_bf16_f32 v21, v18, v19
	v_and_b32_e32 v19, 0xffff0000, v20
	v_lshlrev_b32_e32 v18, 16, v20
	v_mul_f32_e32 v19, v19, v19
	v_cvt_pk_bf16_f32 v22, v24, v25
	v_and_b32_e32 v25, 0xffff0000, v21
	v_fmac_f32_e32 v19, v18, v18
	v_lshlrev_b32_e32 v24, 16, v21
	v_add_f32_e32 v18, v19, v34
	v_mul_f32_e32 v19, v25, v25
	v_cvt_pk_bf16_f32 v23, v30, v31
	v_and_b32_e32 v31, 0xffff0000, v22
	v_fmac_f32_e32 v19, v24, v24
	v_lshlrev_b32_e32 v30, 16, v22
	v_add_f32_e32 v18, v19, v18
	v_mul_f32_e32 v19, v31, v31
	v_and_b32_e32 v33, 0xffff0000, v23
	v_fmac_f32_e32 v19, v30, v30
	v_lshlrev_b32_e32 v32, 16, v23
	v_add_f32_e32 v18, v19, v18
	v_mul_f32_e32 v19, v33, v33
	v_fmac_f32_e32 v19, v32, v32
	v_add_f32_e32 v18, v19, v18
	v_mov_b32_e32 v19, v18
	s_nop 1
	v_permlane16_swap_b32_e32 v19, v18
	v_lshlrev_b64 v[24:25], 11, v[134:135]
	v_lshl_add_u64 v[24:25], s[92:93], 0, v[24:25]
	v_lshl_add_u64 v[24:25], v[204:205], 1, v[24:25]
	global_store_dwordx4 v[24:25], v[26:29], off
	global_store_dwordx4 v[24:25], v[20:23], off offset:256
	s_waitcnt lgkmcnt(0)
	v_add_f32_e32 v18, v18, v19
	v_mov_b32_e32 v19, v18
	s_nop 1
	v_permlane32_swap_b32_e32 v19, v18
	s_and_saveexec_b64 s[10:11], vcc
	s_cbranch_execz .LBB0_962
	s_lshl_b32 s20, s82, 2
	v_lshl_add_u64 v[20:21], s[4:5], 0, v[136:137]
	s_ashr_i32 s21, s20, 31
	v_lshl_add_u64 v[20:21], s[20:21], 2, v[20:21]
	s_lshl_b32 s76, s19, 2
	v_lshl_add_u64 v[20:21], v[20:21], 0, s[76:77]
	s_waitcnt lgkmcnt(0)
	v_add_f32_e32 v18, v18, v19
	global_store_dword v[20:21], v18, off
.LBB0_962:
	s_or_b64 exec, exec, s[10:11]
	v_add_f32_e32 v18, v146, v147
	v_fmamk_f32 v18, v18, 0x3a800000, v240
	v_rsq_f32_e32 v22, v18
	s_waitcnt vmcnt(11)
	v_lshlrev_b32_e32 v20, 16, v74
	v_and_b32_e32 v21, 0xffff0000, v74
	v_mul_f32_e32 v14, v14, v22
	v_mul_f32_e32 v15, v15, v22
	v_mul_f32_e32 v14, 0xbfb8aa3b, v14
	v_mul_f32_e32 v15, 0xbfb8aa3b, v15
	v_mul_f32_e32 v16, v16, v22
	v_mul_f32_e32 v17, v17, v22
	v_exp_f32_e32 v18, v14
	v_exp_f32_e32 v15, v15
	v_mul_f32_e32 v16, 0xbfb8aa3b, v16
	v_mul_f32_e32 v17, 0xbfb8aa3b, v17
	v_mul_f32_e32 v10, v10, v22
	v_mul_f32_e32 v11, v11, v22
	v_exp_f32_e32 v16, v16
	v_exp_f32_e32 v17, v17
	v_mul_f32_e32 v10, 0xbfb8aa3b, v10
	v_mul_f32_e32 v11, 0xbfb8aa3b, v11
	v_exp_f32_e32 v10, v10
	v_exp_f32_e32 v11, v11
	v_mul_f32_e32 v12, v12, v22
	v_add_f32_e32 v18, 1.0, v18
	v_add_f32_e32 v15, 1.0, v15
	v_mul_f32_e32 v12, 0xbfb8aa3b, v12
	v_rcp_f32_e32 v18, v18
	s_waitcnt lgkmcnt(0)
	v_rcp_f32_e32 v19, v15
	v_add_f32_e32 v16, 1.0, v16
	v_add_f32_e32 v17, 1.0, v17
	v_exp_f32_e32 v23, v12
	v_mul_f32_e32 v12, v13, v22
	v_rcp_f32_e32 v16, v16
	v_rcp_f32_e32 v17, v17
	v_add_f32_e32 v10, 1.0, v10
	v_add_f32_e32 v11, 1.0, v11
	v_mul_f32_e32 v12, 0xbfb8aa3b, v12
	v_rcp_f32_e32 v10, v10
	v_rcp_f32_e32 v11, v11
	v_exp_f32_e32 v24, v12
	v_lshlrev_b32_e32 v14, 16, v78
	v_and_b32_e32 v15, 0xffff0000, v78
	v_pk_fma_f32 v[14:15], v[18:19], v[20:21], v[14:15]
	v_lshlrev_b32_e32 v18, 16, v79
	v_and_b32_e32 v19, 0xffff0000, v79
	v_lshlrev_b32_e32 v20, 16, v75
	v_and_b32_e32 v21, 0xffff0000, v75
	v_pk_fma_f32 v[16:17], v[16:17], v[20:21], v[18:19]
	v_lshlrev_b32_e32 v18, 16, v80
	v_and_b32_e32 v19, 0xffff0000, v80
	v_lshlrev_b32_e32 v20, 16, v76
	v_and_b32_e32 v21, 0xffff0000, v76
	v_pk_fma_f32 v[12:13], v[10:11], v[20:21], v[18:19]
	v_add_f32_e32 v10, 1.0, v23
	v_add_f32_e32 v11, 1.0, v24
	v_rcp_f32_e32 v10, v10
	v_rcp_f32_e32 v11, v11
	v_lshlrev_b32_e32 v18, 16, v81
	v_and_b32_e32 v19, 0xffff0000, v81
	v_lshlrev_b32_e32 v20, 16, v77
	v_and_b32_e32 v21, 0xffff0000, v77
	v_pk_fma_f32 v[18:19], v[10:11], v[20:21], v[18:19]
	v_cvt_pk_bf16_f32 v10, v14, v15
	v_mul_f32_e32 v6, v6, v22
	v_mul_f32_e32 v7, v7, v22
	v_cvt_pk_bf16_f32 v11, v16, v17
	v_and_b32_e32 v15, 0xffff0000, v10
	v_mul_f32_e32 v6, 0xbfb8aa3b, v6
	v_mul_f32_e32 v7, 0xbfb8aa3b, v7
	v_mul_f32_e32 v8, v8, v22
	v_mul_f32_e32 v9, v9, v22
	v_lshlrev_b32_e32 v14, 16, v10
	v_and_b32_e32 v17, 0xffff0000, v11
	v_mul_f32_e32 v15, v15, v15
	v_exp_f32_e32 v6, v6
	v_exp_f32_e32 v7, v7
	v_mul_f32_e32 v8, 0xbfb8aa3b, v8
	v_mul_f32_e32 v9, 0xbfb8aa3b, v9
	v_cvt_pk_bf16_f32 v12, v12, v13
	v_lshlrev_b32_e32 v16, 16, v11
	v_fmac_f32_e32 v15, v14, v14
	v_mul_f32_e32 v14, v17, v17
	v_exp_f32_e32 v8, v8
	v_exp_f32_e32 v9, v9
	v_cvt_pk_bf16_f32 v13, v18, v19
	v_and_b32_e32 v19, 0xffff0000, v12
	v_fmac_f32_e32 v14, v16, v16
	v_mul_f32_e32 v2, v2, v22
	v_lshlrev_b32_e32 v18, 16, v12
	v_add_f32_e32 v14, v15, v14
	v_mul_f32_e32 v15, v19, v19
	v_mul_f32_e32 v2, 0xbfb8aa3b, v2
	v_and_b32_e32 v21, 0xffff0000, v13
	v_fmac_f32_e32 v15, v18, v18
	v_add_f32_e32 v6, 1.0, v6
	v_add_f32_e32 v7, 1.0, v7
	v_exp_f32_e32 v19, v2
	v_mul_f32_e32 v2, v3, v22
	v_lshlrev_b32_e32 v20, 16, v13
	v_add_f32_e32 v14, v15, v14
	v_mul_f32_e32 v15, v21, v21
	v_rcp_f32_e32 v6, v6
	v_rcp_f32_e32 v7, v7
	v_add_f32_e32 v8, 1.0, v8
	v_add_f32_e32 v9, 1.0, v9
	v_mul_f32_e32 v2, 0xbfb8aa3b, v2
	v_mul_f32_e32 v4, v4, v22
	v_mul_f32_e32 v5, v5, v22
	v_fmac_f32_e32 v15, v20, v20
	v_rcp_f32_e32 v8, v8
	v_rcp_f32_e32 v9, v9
	v_exp_f32_e32 v20, v2
	v_mul_f32_e32 v4, 0xbfb8aa3b, v4
	v_mul_f32_e32 v5, 0xbfb8aa3b, v5
	v_exp_f32_e32 v4, v4
	v_exp_f32_e32 v5, v5
	v_add_f32_e32 v18, v15, v14
	s_waitcnt vmcnt(10)
	v_lshlrev_b32_e32 v14, 16, v70
	v_and_b32_e32 v15, 0xffff0000, v70
	s_waitcnt vmcnt(9)
	v_lshlrev_b32_e32 v16, 16, v66
	v_and_b32_e32 v17, 0xffff0000, v66
	v_pk_fma_f32 v[6:7], v[6:7], v[16:17], v[14:15]
	v_lshlrev_b32_e32 v14, 16, v71
	v_and_b32_e32 v15, 0xffff0000, v71
	v_lshlrev_b32_e32 v16, 16, v67
	v_and_b32_e32 v17, 0xffff0000, v67
	v_pk_fma_f32 v[2:3], v[8:9], v[16:17], v[14:15]
	v_add_f32_e32 v8, 1.0, v19
	v_add_f32_e32 v9, 1.0, v20
	v_rcp_f32_e32 v8, v8
	v_rcp_f32_e32 v9, v9
	v_add_f32_e32 v4, 1.0, v4
	v_add_f32_e32 v5, 1.0, v5
	v_rcp_f32_e32 v4, v4
	v_rcp_f32_e32 v5, v5
	v_lshlrev_b32_e32 v14, 16, v72
	v_and_b32_e32 v15, 0xffff0000, v72
	v_lshlrev_b32_e32 v16, 16, v68
	v_and_b32_e32 v17, 0xffff0000, v68
	v_pk_fma_f32 v[8:9], v[8:9], v[16:17], v[14:15]
	v_lshlrev_b32_e32 v14, 16, v73
	v_and_b32_e32 v15, 0xffff0000, v73
	v_lshlrev_b32_e32 v16, 16, v69
	v_and_b32_e32 v17, 0xffff0000, v69
	v_pk_fma_f32 v[14:15], v[4:5], v[16:17], v[14:15]
	v_cvt_pk_bf16_f32 v4, v6, v7
	v_cvt_pk_bf16_f32 v5, v2, v3
	v_and_b32_e32 v3, 0xffff0000, v4
	v_lshlrev_b32_e32 v2, 16, v4
	v_mul_f32_e32 v3, v3, v3
	v_cvt_pk_bf16_f32 v6, v8, v9
	v_and_b32_e32 v9, 0xffff0000, v5
	v_fmac_f32_e32 v3, v2, v2
	v_lshlrev_b32_e32 v8, 16, v5
	v_add_f32_e32 v2, v3, v18
	v_mul_f32_e32 v3, v9, v9
	v_cvt_pk_bf16_f32 v7, v14, v15
	v_and_b32_e32 v15, 0xffff0000, v6
	v_fmac_f32_e32 v3, v8, v8
	v_lshlrev_b32_e32 v14, 16, v6
	v_add_f32_e32 v2, v3, v2
	v_mul_f32_e32 v3, v15, v15
	v_and_b32_e32 v17, 0xffff0000, v7
	v_fmac_f32_e32 v3, v14, v14
	v_lshlrev_b32_e32 v16, 16, v7
	v_add_f32_e32 v2, v3, v2
	v_mul_f32_e32 v3, v17, v17
	v_fmac_f32_e32 v3, v16, v16
	v_add_f32_e32 v2, v3, v2
	v_mov_b32_e32 v3, v2
	s_nop 1
	v_permlane16_swap_b32_e32 v3, v2
	v_lshlrev_b64 v[8:9], 11, v[130:131]
	v_lshl_add_u64 v[8:9], s[92:93], 0, v[8:9]
	v_lshl_add_u64 v[8:9], v[204:205], 1, v[8:9]
	global_store_dwordx4 v[8:9], v[10:13], off
	global_store_dwordx4 v[8:9], v[4:7], off offset:256
	s_waitcnt lgkmcnt(0)
	v_add_f32_e32 v2, v2, v3
	v_mov_b32_e32 v3, v2
	s_nop 1
	v_permlane32_swap_b32_e32 v3, v2
	s_and_saveexec_b64 s[10:11], vcc
	s_cbranch_execz .LBB0_964
	s_lshl_b32 s20, s82, 2
	v_lshl_add_u64 v[4:5], s[4:5], 0, v[132:133]
	s_ashr_i32 s21, s20, 31
	v_lshl_add_u64 v[4:5], s[20:21], 2, v[4:5]
	s_lshl_b32 s76, s19, 2
	v_lshl_add_u64 v[4:5], v[4:5], 0, s[76:77]
	s_waitcnt lgkmcnt(0)
	v_add_f32_e32 v2, v2, v3
	global_store_dword v[4:5], v2, off
